# v59 + deleted 24 always-satisfied lgkmcnt(0) waits at GEMM MMA segment starts
# speedup vs baseline: 1.0067x; 1.0029x over previous
.LBB0_46:
	s_add_u32 s0, s4, s8
	s_addc_u32 s1, s5, s9
	s_add_u32 s10, s0, 0x100
	s_addc_u32 s11, s1, 0
	s_add_u32 s55, s19, s8
	s_addc_u32 s96, s31, s9
	s_add_i32 s97, 16, 0x10000
	s_cmpk_eq_i32 s8, 0x700
	s_cselect_b64 s[48:49], -1, 0
	s_and_b64 s[0:1], s[48:49], exec
	s_cselect_b32 s47, s35, s11
	s_cselect_b32 s46, s52, s10
	s_cselect_b32 s11, s12, s96
	s_cselect_b32 s10, s13, s55
	s_add_i32 s55, 16, 0x14000
	v_add_u32_e32 v128, s97, v203
	v_add_u32_e32 v140, s55, v203
	ds_read_b128 v[144:147], v128
	ds_read_b128 v[148:151], v128 offset:1024
	ds_read_b128 v[152:155], v128 offset:2048
	ds_read_b128 v[156:159], v128 offset:3072
	ds_read_b128 v[128:131], v140
	ds_read_b128 v[132:135], v140 offset:1024
	ds_read_b128 v[136:139], v140 offset:2048
	ds_read_b128 v[140:143], v140 offset:3072
	v_lshl_add_u64 v[214:215], v[212:213], 0, s[8:9]
	s_add_i32 m0, s43, 0xc000
	s_waitcnt lgkmcnt(0)
	ds_read_b128 v[162:165], v223
	ds_read_b128 v[166:169], v223 offset:1024
	ds_read_b128 v[170:173], v223 offset:2048
	ds_read_b128 v[174:177], v223 offset:3072
	ds_read_b128 v[178:181], v223 offset:4096
	ds_read_b128 v[182:185], v223 offset:5120
	ds_read_b128 v[186:189], v223 offset:6144
	ds_read_b128 v[190:193], v223 offset:7168
	global_load_lds_dwordx4 v[214:215], off
	v_lshl_add_u64 v[214:215], v[210:211], 0, s[8:9]
	s_add_i32 m0, s43, 0xe000
	s_nop 0
	global_load_lds_dwordx4 v[214:215], off
	s_waitcnt vmcnt(8)
	s_waitcnt lgkmcnt(0)
	s_barrier
	s_setprio 1
	v_mfma_f32_16x16x32_bf16 v[124:127], v[144:147], v[162:165], v[124:127]
	v_mfma_f32_16x16x32_bf16 v[120:123], v[152:155], v[162:165], v[120:123]
	v_mfma_f32_16x16x32_bf16 v[108:111], v[144:147], v[170:173], v[108:111]
	v_mfma_f32_16x16x32_bf16 v[104:107], v[152:155], v[170:173], v[104:107]
	v_mfma_f32_16x16x32_bf16 v[92:95], v[144:147], v[178:181], v[92:95]
	v_mfma_f32_16x16x32_bf16 v[88:91], v[152:155], v[178:181], v[88:91]
	v_mfma_f32_16x16x32_bf16 v[76:79], v[144:147], v[186:189], v[76:79]
	v_mfma_f32_16x16x32_bf16 v[72:75], v[152:155], v[186:189], v[72:75]
	v_mfma_f32_16x16x32_bf16 v[124:127], v[148:151], v[166:169], v[124:127]
	v_mfma_f32_16x16x32_bf16 v[120:123], v[156:159], v[166:169], v[120:123]
	v_mfma_f32_16x16x32_bf16 v[108:111], v[148:151], v[174:177], v[108:111]
	v_mfma_f32_16x16x32_bf16 v[104:107], v[156:159], v[174:177], v[104:107]
	v_mfma_f32_16x16x32_bf16 v[92:95], v[148:151], v[182:185], v[92:95]
	v_mfma_f32_16x16x32_bf16 v[88:91], v[156:159], v[182:185], v[88:91]
	v_mfma_f32_16x16x32_bf16 v[76:79], v[148:151], v[190:193], v[76:79]
	v_mfma_f32_16x16x32_bf16 v[72:75], v[156:159], v[190:193], v[72:75]
	s_setprio 0
	s_setprio 1
	v_mfma_f32_16x16x32_bf16 v[116:119], v[128:131], v[162:165], v[116:119]
	v_mfma_f32_16x16x32_bf16 v[112:115], v[136:139], v[162:165], v[112:115]
	v_mfma_f32_16x16x32_bf16 v[100:103], v[128:131], v[170:173], v[100:103]
	v_mfma_f32_16x16x32_bf16 v[96:99], v[136:139], v[170:173], v[96:99]
	v_mfma_f32_16x16x32_bf16 v[84:87], v[128:131], v[178:181], v[84:87]
	v_mfma_f32_16x16x32_bf16 v[80:83], v[136:139], v[178:181], v[80:83]
	v_mfma_f32_16x16x32_bf16 v[68:71], v[128:131], v[186:189], v[68:71]
	v_mfma_f32_16x16x32_bf16 v[64:67], v[136:139], v[186:189], v[64:67]
	v_mfma_f32_16x16x32_bf16 v[116:119], v[132:135], v[166:169], v[116:119]
	v_mfma_f32_16x16x32_bf16 v[112:115], v[140:143], v[166:169], v[112:115]
	v_mfma_f32_16x16x32_bf16 v[100:103], v[132:135], v[174:177], v[100:103]
	v_mfma_f32_16x16x32_bf16 v[96:99], v[140:143], v[174:177], v[96:99]
	v_mfma_f32_16x16x32_bf16 v[84:87], v[132:135], v[182:185], v[84:87]
	v_mfma_f32_16x16x32_bf16 v[80:83], v[140:143], v[182:185], v[80:83]
	v_mfma_f32_16x16x32_bf16 v[68:71], v[132:135], v[190:193], v[68:71]
	v_mfma_f32_16x16x32_bf16 v[64:67], v[140:143], v[190:193], v[64:67]
	s_setprio 0
	s_barrier
	s_add_i32 s0, s97, s53
	v_lshl_add_u64 v[214:215], s[10:11], 0, v[198:199]
	s_mov_b32 m0, s0
	ds_read_b128 v[186:189], v223 offset:16384
	ds_read_b128 v[190:193], v223 offset:17408
	ds_read_b128 v[178:181], v223 offset:18432
	ds_read_b128 v[182:185], v223 offset:19456
	ds_read_b128 v[170:173], v223 offset:20480
	ds_read_b128 v[174:177], v223 offset:21504
	ds_read_b128 v[162:165], v223 offset:22528
	ds_read_b128 v[166:169], v223 offset:23552
	global_load_lds_dwordx4 v[214:215], off
	s_add_i32 m0, s0, 0x2000
	s_add_u32 s0, s10, 0x40000
	v_lshl_add_u64 v[216:217], s[10:11], 0, v[194:195]
	s_addc_u32 s1, s11, 0
	s_add_i32 s55, s55, s53
	global_load_lds_dwordx4 v[216:217], off
	v_lshl_add_u64 v[218:219], s[0:1], 0, v[198:199]
	s_mov_b32 m0, s55
	v_lshl_add_u64 v[220:221], s[46:47], 0, v[196:197]
	global_load_lds_dwordx4 v[218:219], off
	v_lshl_add_u64 v[218:219], s[0:1], 0, v[194:195]
	s_add_i32 m0, s55, 0x2000
	v_cndmask_b32_e64 v160, 0, 1, s[6:7]
	global_load_lds_dwordx4 v[218:219], off
	v_lshl_add_u64 v[218:219], s[46:47], 0, v[200:201]
	s_mov_b32 m0, s43
	v_cmp_ne_u32_e64 s[0:1], 1, v160
	global_load_lds_dwordx4 v[218:219], off
	s_mov_b32 m0, s45
	s_andn2_b64 vcc, exec, s[6:7]
	global_load_lds_dwordx4 v[220:221], off
	s_waitcnt vmcnt(8)
	s_waitcnt lgkmcnt(0)
	s_barrier
	s_cbranch_vccnz .LBB0_48
	s_setprio 1
	v_mfma_f32_16x16x32_bf16 v[60:63], v[144:147], v[186:189], v[60:63]
	v_mfma_f32_16x16x32_bf16 v[56:59], v[152:155], v[186:189], v[56:59]
	v_mfma_f32_16x16x32_bf16 v[44:47], v[144:147], v[178:181], v[44:47]
	v_mfma_f32_16x16x32_bf16 v[40:43], v[152:155], v[178:181], v[40:43]
	v_mfma_f32_16x16x32_bf16 v[28:31], v[144:147], v[170:173], v[28:31]
	v_mfma_f32_16x16x32_bf16 v[24:27], v[152:155], v[170:173], v[24:27]
	v_mfma_f32_16x16x32_bf16 v[12:15], v[144:147], v[162:165], v[12:15]
	v_mfma_f32_16x16x32_bf16 v[8:11], v[152:155], v[162:165], v[8:11]
	v_mfma_f32_16x16x32_bf16 v[60:63], v[148:151], v[190:193], v[60:63]
	v_mfma_f32_16x16x32_bf16 v[56:59], v[156:159], v[190:193], v[56:59]
	v_mfma_f32_16x16x32_bf16 v[44:47], v[148:151], v[182:185], v[44:47]
	v_mfma_f32_16x16x32_bf16 v[40:43], v[156:159], v[182:185], v[40:43]
	v_mfma_f32_16x16x32_bf16 v[28:31], v[148:151], v[174:177], v[28:31]
	v_mfma_f32_16x16x32_bf16 v[24:27], v[156:159], v[174:177], v[24:27]
	v_mfma_f32_16x16x32_bf16 v[12:15], v[148:151], v[166:169], v[12:15]
	v_mfma_f32_16x16x32_bf16 v[8:11], v[156:159], v[166:169], v[8:11]
	s_setprio 0
	s_setprio 1
	v_mfma_f32_16x16x32_bf16 v[52:55], v[128:131], v[186:189], v[52:55]
	v_mfma_f32_16x16x32_bf16 v[48:51], v[136:139], v[186:189], v[48:51]
	v_mfma_f32_16x16x32_bf16 v[36:39], v[128:131], v[178:181], v[36:39]
	v_mfma_f32_16x16x32_bf16 v[32:35], v[136:139], v[178:181], v[32:35]
	v_mfma_f32_16x16x32_bf16 v[20:23], v[128:131], v[170:173], v[20:23]
	v_mfma_f32_16x16x32_bf16 v[16:19], v[136:139], v[170:173], v[16:19]
	v_mfma_f32_16x16x32_bf16 v[4:7], v[128:131], v[162:165], v[4:7]
	v_mfma_f32_16x16x32_bf16 v[0:3], v[136:139], v[162:165], v[0:3]
	v_mfma_f32_16x16x32_bf16 v[52:55], v[132:135], v[190:193], v[52:55]
	v_mfma_f32_16x16x32_bf16 v[48:51], v[140:143], v[190:193], v[48:51]
	v_mfma_f32_16x16x32_bf16 v[36:39], v[132:135], v[182:185], v[36:39]
	v_mfma_f32_16x16x32_bf16 v[32:35], v[140:143], v[182:185], v[32:35]
	v_mfma_f32_16x16x32_bf16 v[20:23], v[132:135], v[174:177], v[20:23]
	v_mfma_f32_16x16x32_bf16 v[16:19], v[140:143], v[174:177], v[16:19]
	v_mfma_f32_16x16x32_bf16 v[4:7], v[132:135], v[166:169], v[4:7]
	v_mfma_f32_16x16x32_bf16 v[0:3], v[140:143], v[166:169], v[0:3]
	s_setprio 0
.LBB0_48:
	s_barrier
	s_add_i32 s55, 16, 0x18000
	s_add_i32 s96, 16, 0x1c000
	v_add_u32_e32 v128, s55, v203
	v_add_u32_e32 v140, s96, v203
	ds_read_b128 v[144:147], v128
	ds_read_b128 v[148:151], v128 offset:1024
	ds_read_b128 v[152:155], v128 offset:2048
	ds_read_b128 v[156:159], v128 offset:3072
	ds_read_b128 v[128:131], v140
	ds_read_b128 v[132:135], v140 offset:1024
	ds_read_b128 v[136:139], v140 offset:2048
	ds_read_b128 v[140:143], v140 offset:3072
	s_and_b64 s[48:49], s[40:41], s[48:49]
	s_and_b64 s[48:49], s[48:49], exec
	s_cselect_b32 s49, s18, s64
	s_cselect_b32 s48, 0, 0
	s_add_u32 s46, s46, s49
	s_addc_u32 s47, s47, s48
	s_mov_b32 m0, s14
	v_lshl_add_u64 v[224:225], s[46:47], 0, v[200:201]
	s_waitcnt lgkmcnt(0)
	ds_read_b128 v[162:165], v223 offset:32768
	ds_read_b128 v[166:169], v223 offset:33792
	ds_read_b128 v[170:173], v223 offset:34816
	ds_read_b128 v[174:177], v223 offset:35840
	ds_read_b128 v[178:181], v223 offset:36864
	ds_read_b128 v[182:185], v223 offset:37888
	ds_read_b128 v[186:189], v223 offset:38912
	ds_read_b128 v[190:193], v223 offset:39936
	global_load_lds_dwordx4 v[224:225], off
	v_lshl_add_u64 v[224:225], s[46:47], 0, v[196:197]
	s_mov_b32 m0, s16
	s_nop 0
	global_load_lds_dwordx4 v[224:225], off
	s_waitcnt vmcnt(8)
	s_waitcnt lgkmcnt(0)
	s_barrier
	s_setprio 1
	v_mfma_f32_16x16x32_bf16 v[124:127], v[144:147], v[162:165], v[124:127]
	v_mfma_f32_16x16x32_bf16 v[120:123], v[152:155], v[162:165], v[120:123]
	v_mfma_f32_16x16x32_bf16 v[108:111], v[144:147], v[170:173], v[108:111]
	v_mfma_f32_16x16x32_bf16 v[104:107], v[152:155], v[170:173], v[104:107]
	v_mfma_f32_16x16x32_bf16 v[92:95], v[144:147], v[178:181], v[92:95]
	v_mfma_f32_16x16x32_bf16 v[88:91], v[152:155], v[178:181], v[88:91]
	v_mfma_f32_16x16x32_bf16 v[76:79], v[144:147], v[186:189], v[76:79]
	v_mfma_f32_16x16x32_bf16 v[72:75], v[152:155], v[186:189], v[72:75]
	v_mfma_f32_16x16x32_bf16 v[124:127], v[148:151], v[166:169], v[124:127]
	v_mfma_f32_16x16x32_bf16 v[120:123], v[156:159], v[166:169], v[120:123]
	v_mfma_f32_16x16x32_bf16 v[108:111], v[148:151], v[174:177], v[108:111]
	v_mfma_f32_16x16x32_bf16 v[104:107], v[156:159], v[174:177], v[104:107]
	v_mfma_f32_16x16x32_bf16 v[92:95], v[148:151], v[182:185], v[92:95]
	v_mfma_f32_16x16x32_bf16 v[88:91], v[156:159], v[182:185], v[88:91]
	v_mfma_f32_16x16x32_bf16 v[76:79], v[148:151], v[190:193], v[76:79]
	v_mfma_f32_16x16x32_bf16 v[72:75], v[156:159], v[190:193], v[72:75]
	s_setprio 0
	s_setprio 1
	v_mfma_f32_16x16x32_bf16 v[116:119], v[128:131], v[162:165], v[116:119]
	v_mfma_f32_16x16x32_bf16 v[112:115], v[136:139], v[162:165], v[112:115]
	v_mfma_f32_16x16x32_bf16 v[100:103], v[128:131], v[170:173], v[100:103]
	v_mfma_f32_16x16x32_bf16 v[96:99], v[136:139], v[170:173], v[96:99]
	v_mfma_f32_16x16x32_bf16 v[84:87], v[128:131], v[178:181], v[84:87]
	v_mfma_f32_16x16x32_bf16 v[80:83], v[136:139], v[178:181], v[80:83]
	v_mfma_f32_16x16x32_bf16 v[68:71], v[128:131], v[186:189], v[68:71]
	v_mfma_f32_16x16x32_bf16 v[64:67], v[136:139], v[186:189], v[64:67]
	v_mfma_f32_16x16x32_bf16 v[116:119], v[132:135], v[166:169], v[116:119]
	v_mfma_f32_16x16x32_bf16 v[112:115], v[140:143], v[166:169], v[112:115]
	v_mfma_f32_16x16x32_bf16 v[100:103], v[132:135], v[174:177], v[100:103]
	v_mfma_f32_16x16x32_bf16 v[96:99], v[140:143], v[174:177], v[96:99]
	v_mfma_f32_16x16x32_bf16 v[84:87], v[132:135], v[182:185], v[84:87]
	v_mfma_f32_16x16x32_bf16 v[80:83], v[140:143], v[182:185], v[80:83]
	v_mfma_f32_16x16x32_bf16 v[68:71], v[132:135], v[190:193], v[68:71]
	v_mfma_f32_16x16x32_bf16 v[64:67], v[140:143], v[190:193], v[64:67]
	s_setprio 0
	s_barrier
	s_add_i32 s46, s55, s53
	v_lshl_add_u64 v[214:215], v[214:215], 0, s[84:85]
	s_mov_b32 m0, s46
	ds_read_b128 v[186:189], v223 offset:49152
	ds_read_b128 v[190:193], v223 offset:50176
	ds_read_b128 v[178:181], v223 offset:51200
	ds_read_b128 v[182:185], v223 offset:52224
	ds_read_b128 v[170:173], v223 offset:53248
	ds_read_b128 v[174:177], v223 offset:54272
	ds_read_b128 v[162:165], v223 offset:55296
	ds_read_b128 v[166:169], v223 offset:56320
	global_load_lds_dwordx4 v[214:215], off
	s_add_i32 m0, s46, 0x2000
	s_add_u32 s10, s10, 0x40080
	v_lshl_add_u64 v[214:215], v[216:217], 0, s[84:85]
	s_addc_u32 s11, s11, 0
	s_add_i32 s46, s96, s53
	global_load_lds_dwordx4 v[214:215], off
	v_lshl_add_u64 v[214:215], s[10:11], 0, v[198:199]
	s_mov_b32 m0, s46
	s_and_b64 vcc, exec, s[0:1]
	global_load_lds_dwordx4 v[214:215], off
	v_lshl_add_u64 v[214:215], s[10:11], 0, v[194:195]
	s_add_i32 m0, s46, 0x2000
	s_nop 0
	global_load_lds_dwordx4 v[214:215], off
	v_lshl_add_u64 v[214:215], v[218:219], 0, s[84:85]
	s_mov_b32 m0, s17
	s_nop 0
	global_load_lds_dwordx4 v[214:215], off
	v_lshl_add_u64 v[214:215], v[220:221], 0, s[84:85]
	s_mov_b32 m0, s15
	s_nop 0
	global_load_lds_dwordx4 v[214:215], off
	s_waitcnt vmcnt(8)
	s_waitcnt lgkmcnt(0)
	s_barrier
	s_cbranch_vccnz .LBB0_45
	s_setprio 1
	v_mfma_f32_16x16x32_bf16 v[60:63], v[144:147], v[186:189], v[60:63]
	v_mfma_f32_16x16x32_bf16 v[56:59], v[152:155], v[186:189], v[56:59]
	v_mfma_f32_16x16x32_bf16 v[44:47], v[144:147], v[178:181], v[44:47]
	v_mfma_f32_16x16x32_bf16 v[40:43], v[152:155], v[178:181], v[40:43]
	v_mfma_f32_16x16x32_bf16 v[28:31], v[144:147], v[170:173], v[28:31]
	v_mfma_f32_16x16x32_bf16 v[24:27], v[152:155], v[170:173], v[24:27]
	v_mfma_f32_16x16x32_bf16 v[12:15], v[144:147], v[162:165], v[12:15]
	v_mfma_f32_16x16x32_bf16 v[8:11], v[152:155], v[162:165], v[8:11]
	v_mfma_f32_16x16x32_bf16 v[60:63], v[148:151], v[190:193], v[60:63]
	v_mfma_f32_16x16x32_bf16 v[56:59], v[156:159], v[190:193], v[56:59]
	v_mfma_f32_16x16x32_bf16 v[44:47], v[148:151], v[182:185], v[44:47]
	v_mfma_f32_16x16x32_bf16 v[40:43], v[156:159], v[182:185], v[40:43]
	v_mfma_f32_16x16x32_bf16 v[28:31], v[148:151], v[174:177], v[28:31]
	v_mfma_f32_16x16x32_bf16 v[24:27], v[156:159], v[174:177], v[24:27]
	v_mfma_f32_16x16x32_bf16 v[12:15], v[148:151], v[166:169], v[12:15]
	v_mfma_f32_16x16x32_bf16 v[8:11], v[156:159], v[166:169], v[8:11]
	s_setprio 0
	s_setprio 1
	v_mfma_f32_16x16x32_bf16 v[52:55], v[128:131], v[186:189], v[52:55]
	v_mfma_f32_16x16x32_bf16 v[48:51], v[136:139], v[186:189], v[48:51]
	v_mfma_f32_16x16x32_bf16 v[36:39], v[128:131], v[178:181], v[36:39]
	v_mfma_f32_16x16x32_bf16 v[32:35], v[136:139], v[178:181], v[32:35]
	v_mfma_f32_16x16x32_bf16 v[20:23], v[128:131], v[170:173], v[20:23]
	v_mfma_f32_16x16x32_bf16 v[16:19], v[136:139], v[170:173], v[16:19]
	v_mfma_f32_16x16x32_bf16 v[4:7], v[128:131], v[162:165], v[4:7]
	v_mfma_f32_16x16x32_bf16 v[0:3], v[136:139], v[162:165], v[0:3]
	v_mfma_f32_16x16x32_bf16 v[52:55], v[132:135], v[190:193], v[52:55]
	v_mfma_f32_16x16x32_bf16 v[48:51], v[140:143], v[190:193], v[48:51]
	v_mfma_f32_16x16x32_bf16 v[36:39], v[132:135], v[182:185], v[36:39]
	v_mfma_f32_16x16x32_bf16 v[32:35], v[140:143], v[182:185], v[32:35]
	v_mfma_f32_16x16x32_bf16 v[20:23], v[132:135], v[174:177], v[20:23]
	v_mfma_f32_16x16x32_bf16 v[16:19], v[140:143], v[174:177], v[16:19]
	v_mfma_f32_16x16x32_bf16 v[4:7], v[132:135], v[166:169], v[4:7]
	v_mfma_f32_16x16x32_bf16 v[0:3], v[140:143], v[166:169], v[0:3]
	s_setprio 0
	s_branch .LBB0_45

.LBB0_81:
	s_add_u32 s6, s2, s4
	s_addc_u32 s7, s3, s5
	s_add_u32 s8, s6, 0x100
	s_addc_u32 s9, s7, 0
	s_add_u32 s43, s21, s4
	s_addc_u32 s48, s29, s5
	s_add_i32 s49, 16, 0x10000
	s_cmpk_eq_i32 s4, 0x700
	s_cselect_b64 s[10:11], -1, 0
	s_and_b64 s[6:7], s[10:11], exec
	s_cselect_b32 s9, s14, s9
	s_cselect_b32 s8, s15, s8
	s_cselect_b32 s7, s12, s48
	s_cselect_b32 s6, s13, s43
	s_add_i32 s43, 16, 0x14000
	v_add_u32_e32 v128, s49, v205
	v_add_u32_e32 v140, s43, v205
	ds_read_b128 v[144:147], v128
	ds_read_b128 v[148:151], v128 offset:1024
	ds_read_b128 v[152:155], v128 offset:2048
	ds_read_b128 v[156:159], v128 offset:3072
	ds_read_b128 v[128:131], v140
	ds_read_b128 v[132:135], v140 offset:1024
	ds_read_b128 v[136:139], v140 offset:2048
	ds_read_b128 v[140:143], v140 offset:3072
	v_lshl_add_u64 v[228:229], v[226:227], 0, s[4:5]
	s_add_i32 m0, s44, 0xc000
	s_waitcnt lgkmcnt(0)
	ds_read_b128 v[162:165], v241
	ds_read_b128 v[166:169], v241 offset:1024
	ds_read_b128 v[170:173], v241 offset:2048
	ds_read_b128 v[174:177], v241 offset:3072
	ds_read_b128 v[178:181], v241 offset:4096
	ds_read_b128 v[182:185], v241 offset:5120
	ds_read_b128 v[186:189], v241 offset:6144
	ds_read_b128 v[190:193], v241 offset:7168
	global_load_lds_dwordx4 v[228:229], off
	v_lshl_add_u64 v[228:229], v[224:225], 0, s[4:5]
	s_add_i32 m0, s44, 0xe000
	s_nop 0
	global_load_lds_dwordx4 v[228:229], off
	s_waitcnt vmcnt(8)
	s_waitcnt lgkmcnt(0)
	s_barrier
	s_setprio 1
	v_mfma_f32_16x16x32_bf16 v[124:127], v[144:147], v[162:165], v[124:127]
	v_mfma_f32_16x16x32_bf16 v[120:123], v[152:155], v[162:165], v[120:123]
	v_mfma_f32_16x16x32_bf16 v[108:111], v[144:147], v[170:173], v[108:111]
	v_mfma_f32_16x16x32_bf16 v[104:107], v[152:155], v[170:173], v[104:107]
	v_mfma_f32_16x16x32_bf16 v[92:95], v[144:147], v[178:181], v[92:95]
	v_mfma_f32_16x16x32_bf16 v[88:91], v[152:155], v[178:181], v[88:91]
	v_mfma_f32_16x16x32_bf16 v[76:79], v[144:147], v[186:189], v[76:79]
	v_mfma_f32_16x16x32_bf16 v[72:75], v[152:155], v[186:189], v[72:75]
	v_mfma_f32_16x16x32_bf16 v[124:127], v[148:151], v[166:169], v[124:127]
	v_mfma_f32_16x16x32_bf16 v[120:123], v[156:159], v[166:169], v[120:123]
	v_mfma_f32_16x16x32_bf16 v[108:111], v[148:151], v[174:177], v[108:111]
	v_mfma_f32_16x16x32_bf16 v[104:107], v[156:159], v[174:177], v[104:107]
	v_mfma_f32_16x16x32_bf16 v[92:95], v[148:151], v[182:185], v[92:95]
	v_mfma_f32_16x16x32_bf16 v[88:91], v[156:159], v[182:185], v[88:91]
	v_mfma_f32_16x16x32_bf16 v[76:79], v[148:151], v[190:193], v[76:79]
	v_mfma_f32_16x16x32_bf16 v[72:75], v[156:159], v[190:193], v[72:75]
	s_setprio 0
	s_setprio 1
	v_mfma_f32_16x16x32_bf16 v[116:119], v[128:131], v[162:165], v[116:119]
	v_mfma_f32_16x16x32_bf16 v[112:115], v[136:139], v[162:165], v[112:115]
	v_mfma_f32_16x16x32_bf16 v[100:103], v[128:131], v[170:173], v[100:103]
	v_mfma_f32_16x16x32_bf16 v[96:99], v[136:139], v[170:173], v[96:99]
	v_mfma_f32_16x16x32_bf16 v[84:87], v[128:131], v[178:181], v[84:87]
	v_mfma_f32_16x16x32_bf16 v[80:83], v[136:139], v[178:181], v[80:83]
	v_mfma_f32_16x16x32_bf16 v[68:71], v[128:131], v[186:189], v[68:71]
	v_mfma_f32_16x16x32_bf16 v[64:67], v[136:139], v[186:189], v[64:67]
	v_mfma_f32_16x16x32_bf16 v[116:119], v[132:135], v[166:169], v[116:119]
	v_mfma_f32_16x16x32_bf16 v[112:115], v[140:143], v[166:169], v[112:115]
	v_mfma_f32_16x16x32_bf16 v[100:103], v[132:135], v[174:177], v[100:103]
	v_mfma_f32_16x16x32_bf16 v[96:99], v[140:143], v[174:177], v[96:99]
	v_mfma_f32_16x16x32_bf16 v[84:87], v[132:135], v[182:185], v[84:87]
	v_mfma_f32_16x16x32_bf16 v[80:83], v[140:143], v[182:185], v[80:83]
	v_mfma_f32_16x16x32_bf16 v[68:71], v[132:135], v[190:193], v[68:71]
	v_mfma_f32_16x16x32_bf16 v[64:67], v[140:143], v[190:193], v[64:67]
	s_setprio 0
	s_barrier
	s_add_i32 s48, s49, s52
	v_lshl_add_u64 v[228:229], s[6:7], 0, v[194:195]
	s_mov_b32 m0, s48
	ds_read_b128 v[186:189], v241 offset:16384
	ds_read_b128 v[190:193], v241 offset:17408
	ds_read_b128 v[178:181], v241 offset:18432
	ds_read_b128 v[182:185], v241 offset:19456
	ds_read_b128 v[170:173], v241 offset:20480
	ds_read_b128 v[174:177], v241 offset:21504
	ds_read_b128 v[162:165], v241 offset:22528
	ds_read_b128 v[166:169], v241 offset:23552
	global_load_lds_dwordx4 v[228:229], off
	s_add_i32 m0, s48, 0x2000
	s_add_u32 s48, s6, 0x40000
	v_lshl_add_u64 v[230:231], s[6:7], 0, v[196:197]
	s_addc_u32 s49, s7, 0
	s_add_i32 s43, s43, s52
	global_load_lds_dwordx4 v[230:231], off
	v_lshl_add_u64 v[232:233], s[48:49], 0, v[194:195]
	s_mov_b32 m0, s43
	v_lshl_add_u64 v[234:235], s[8:9], 0, v[196:197]
	global_load_lds_dwordx4 v[232:233], off
	v_lshl_add_u64 v[232:233], s[48:49], 0, v[196:197]
	s_add_i32 m0, s43, 0x2000
	v_cndmask_b32_e64 v160, 0, 1, s[0:1]
	global_load_lds_dwordx4 v[232:233], off
	v_lshl_add_u64 v[232:233], s[8:9], 0, v[194:195]
	s_mov_b32 m0, s44
	v_cmp_ne_u32_e64 s[48:49], 1, v160
	global_load_lds_dwordx4 v[232:233], off
	s_mov_b32 m0, s45
	s_andn2_b64 vcc, exec, s[0:1]
	global_load_lds_dwordx4 v[234:235], off
	s_waitcnt vmcnt(8)
	s_waitcnt lgkmcnt(0)
	s_barrier
	s_cbranch_vccnz .LBB0_83
	s_setprio 1
	v_mfma_f32_16x16x32_bf16 v[60:63], v[144:147], v[186:189], v[60:63]
	v_mfma_f32_16x16x32_bf16 v[56:59], v[152:155], v[186:189], v[56:59]
	v_mfma_f32_16x16x32_bf16 v[44:47], v[144:147], v[178:181], v[44:47]
	v_mfma_f32_16x16x32_bf16 v[40:43], v[152:155], v[178:181], v[40:43]
	v_mfma_f32_16x16x32_bf16 v[28:31], v[144:147], v[170:173], v[28:31]
	v_mfma_f32_16x16x32_bf16 v[24:27], v[152:155], v[170:173], v[24:27]
	v_mfma_f32_16x16x32_bf16 v[12:15], v[144:147], v[162:165], v[12:15]
	v_mfma_f32_16x16x32_bf16 v[8:11], v[152:155], v[162:165], v[8:11]
	v_mfma_f32_16x16x32_bf16 v[60:63], v[148:151], v[190:193], v[60:63]
	v_mfma_f32_16x16x32_bf16 v[56:59], v[156:159], v[190:193], v[56:59]
	v_mfma_f32_16x16x32_bf16 v[44:47], v[148:151], v[182:185], v[44:47]
	v_mfma_f32_16x16x32_bf16 v[40:43], v[156:159], v[182:185], v[40:43]
	v_mfma_f32_16x16x32_bf16 v[28:31], v[148:151], v[174:177], v[28:31]
	v_mfma_f32_16x16x32_bf16 v[24:27], v[156:159], v[174:177], v[24:27]
	v_mfma_f32_16x16x32_bf16 v[12:15], v[148:151], v[166:169], v[12:15]
	v_mfma_f32_16x16x32_bf16 v[8:11], v[156:159], v[166:169], v[8:11]
	s_setprio 0
	s_setprio 1
	v_mfma_f32_16x16x32_bf16 v[52:55], v[128:131], v[186:189], v[52:55]
	v_mfma_f32_16x16x32_bf16 v[48:51], v[136:139], v[186:189], v[48:51]
	v_mfma_f32_16x16x32_bf16 v[36:39], v[128:131], v[178:181], v[36:39]
	v_mfma_f32_16x16x32_bf16 v[32:35], v[136:139], v[178:181], v[32:35]
	v_mfma_f32_16x16x32_bf16 v[20:23], v[128:131], v[170:173], v[20:23]
	v_mfma_f32_16x16x32_bf16 v[16:19], v[136:139], v[170:173], v[16:19]
	v_mfma_f32_16x16x32_bf16 v[4:7], v[128:131], v[162:165], v[4:7]
	v_mfma_f32_16x16x32_bf16 v[0:3], v[136:139], v[162:165], v[0:3]
	v_mfma_f32_16x16x32_bf16 v[52:55], v[132:135], v[190:193], v[52:55]
	v_mfma_f32_16x16x32_bf16 v[48:51], v[140:143], v[190:193], v[48:51]
	v_mfma_f32_16x16x32_bf16 v[36:39], v[132:135], v[182:185], v[36:39]
	v_mfma_f32_16x16x32_bf16 v[32:35], v[140:143], v[182:185], v[32:35]
	v_mfma_f32_16x16x32_bf16 v[20:23], v[132:135], v[174:177], v[20:23]
	v_mfma_f32_16x16x32_bf16 v[16:19], v[140:143], v[174:177], v[16:19]
	v_mfma_f32_16x16x32_bf16 v[4:7], v[132:135], v[166:169], v[4:7]
	v_mfma_f32_16x16x32_bf16 v[0:3], v[140:143], v[166:169], v[0:3]
	s_setprio 0
.LBB0_83:
	s_barrier
	s_add_i32 s43, 16, 0x18000
	s_add_i32 s54, 16, 0x1c000
	v_add_u32_e32 v128, s43, v205
	v_add_u32_e32 v140, s54, v205
	ds_read_b128 v[144:147], v128
	ds_read_b128 v[148:151], v128 offset:1024
	ds_read_b128 v[152:155], v128 offset:2048
	ds_read_b128 v[156:159], v128 offset:3072
	ds_read_b128 v[128:131], v140
	ds_read_b128 v[132:135], v140 offset:1024
	ds_read_b128 v[136:139], v140 offset:2048
	ds_read_b128 v[140:143], v140 offset:3072
	s_and_b64 s[10:11], s[46:47], s[10:11]
	s_and_b64 s[10:11], s[10:11], exec
	s_cselect_b32 s11, s20, s64
	s_cselect_b32 s10, 0, 0
	s_add_u32 s8, s8, s11
	s_addc_u32 s9, s9, s10
	s_mov_b32 m0, s30
	v_lshl_add_u64 v[250:251], s[8:9], 0, v[194:195]
	s_waitcnt lgkmcnt(0)
	ds_read_b128 v[162:165], v241 offset:32768
	ds_read_b128 v[166:169], v241 offset:33792
	ds_read_b128 v[170:173], v241 offset:34816
	ds_read_b128 v[174:177], v241 offset:35840
	ds_read_b128 v[178:181], v241 offset:36864
	ds_read_b128 v[182:185], v241 offset:37888
	ds_read_b128 v[186:189], v241 offset:38912
	ds_read_b128 v[190:193], v241 offset:39936
	global_load_lds_dwordx4 v[250:251], off
	v_lshl_add_u64 v[250:251], s[8:9], 0, v[196:197]
	s_mov_b32 m0, s31
	s_nop 0
	global_load_lds_dwordx4 v[250:251], off
	s_waitcnt vmcnt(8)
	s_waitcnt lgkmcnt(0)
	s_barrier
	s_setprio 1
	v_mfma_f32_16x16x32_bf16 v[124:127], v[144:147], v[162:165], v[124:127]
	v_mfma_f32_16x16x32_bf16 v[120:123], v[152:155], v[162:165], v[120:123]
	v_mfma_f32_16x16x32_bf16 v[108:111], v[144:147], v[170:173], v[108:111]
	v_mfma_f32_16x16x32_bf16 v[104:107], v[152:155], v[170:173], v[104:107]
	v_mfma_f32_16x16x32_bf16 v[92:95], v[144:147], v[178:181], v[92:95]
	v_mfma_f32_16x16x32_bf16 v[88:91], v[152:155], v[178:181], v[88:91]
	v_mfma_f32_16x16x32_bf16 v[76:79], v[144:147], v[186:189], v[76:79]
	v_mfma_f32_16x16x32_bf16 v[72:75], v[152:155], v[186:189], v[72:75]
	v_mfma_f32_16x16x32_bf16 v[124:127], v[148:151], v[166:169], v[124:127]
	v_mfma_f32_16x16x32_bf16 v[120:123], v[156:159], v[166:169], v[120:123]
	v_mfma_f32_16x16x32_bf16 v[108:111], v[148:151], v[174:177], v[108:111]
	v_mfma_f32_16x16x32_bf16 v[104:107], v[156:159], v[174:177], v[104:107]
	v_mfma_f32_16x16x32_bf16 v[92:95], v[148:151], v[182:185], v[92:95]
	v_mfma_f32_16x16x32_bf16 v[88:91], v[156:159], v[182:185], v[88:91]
	v_mfma_f32_16x16x32_bf16 v[76:79], v[148:151], v[190:193], v[76:79]
	v_mfma_f32_16x16x32_bf16 v[72:75], v[156:159], v[190:193], v[72:75]
	s_setprio 0
	s_setprio 1
	v_mfma_f32_16x16x32_bf16 v[116:119], v[128:131], v[162:165], v[116:119]
	v_mfma_f32_16x16x32_bf16 v[112:115], v[136:139], v[162:165], v[112:115]
	v_mfma_f32_16x16x32_bf16 v[100:103], v[128:131], v[170:173], v[100:103]
	v_mfma_f32_16x16x32_bf16 v[96:99], v[136:139], v[170:173], v[96:99]
	v_mfma_f32_16x16x32_bf16 v[84:87], v[128:131], v[178:181], v[84:87]
	v_mfma_f32_16x16x32_bf16 v[80:83], v[136:139], v[178:181], v[80:83]
	v_mfma_f32_16x16x32_bf16 v[68:71], v[128:131], v[186:189], v[68:71]
	v_mfma_f32_16x16x32_bf16 v[64:67], v[136:139], v[186:189], v[64:67]
	v_mfma_f32_16x16x32_bf16 v[116:119], v[132:135], v[166:169], v[116:119]
	v_mfma_f32_16x16x32_bf16 v[112:115], v[140:143], v[166:169], v[112:115]
	v_mfma_f32_16x16x32_bf16 v[100:103], v[132:135], v[174:177], v[100:103]
	v_mfma_f32_16x16x32_bf16 v[96:99], v[140:143], v[174:177], v[96:99]
	v_mfma_f32_16x16x32_bf16 v[84:87], v[132:135], v[182:185], v[84:87]
	v_mfma_f32_16x16x32_bf16 v[80:83], v[140:143], v[182:185], v[80:83]
	v_mfma_f32_16x16x32_bf16 v[68:71], v[132:135], v[190:193], v[68:71]
	v_mfma_f32_16x16x32_bf16 v[64:67], v[140:143], v[190:193], v[64:67]
	s_setprio 0
	s_barrier
	s_add_i32 s8, s43, s52
	v_lshl_add_u64 v[228:229], v[228:229], 0, s[84:85]
	s_mov_b32 m0, s8
	ds_read_b128 v[186:189], v241 offset:49152
	ds_read_b128 v[190:193], v241 offset:50176
	ds_read_b128 v[178:181], v241 offset:51200
	ds_read_b128 v[182:185], v241 offset:52224
	ds_read_b128 v[170:173], v241 offset:53248
	ds_read_b128 v[174:177], v241 offset:54272
	ds_read_b128 v[162:165], v241 offset:55296
	ds_read_b128 v[166:169], v241 offset:56320
	global_load_lds_dwordx4 v[228:229], off
	s_add_i32 m0, s8, 0x2000
	s_add_u32 s6, s6, 0x40080
	v_lshl_add_u64 v[228:229], v[230:231], 0, s[84:85]
	s_addc_u32 s7, s7, 0
	s_add_i32 s8, s54, s52
	global_load_lds_dwordx4 v[228:229], off
	v_lshl_add_u64 v[228:229], s[6:7], 0, v[194:195]
	s_mov_b32 m0, s8
	s_and_b64 vcc, exec, s[48:49]
	global_load_lds_dwordx4 v[228:229], off
	v_lshl_add_u64 v[228:229], s[6:7], 0, v[196:197]
	s_add_i32 m0, s8, 0x2000
	s_nop 0
	global_load_lds_dwordx4 v[228:229], off
	v_lshl_add_u64 v[228:229], v[232:233], 0, s[84:85]
	s_mov_b32 m0, s53
	s_nop 0
	global_load_lds_dwordx4 v[228:229], off
	v_lshl_add_u64 v[228:229], v[234:235], 0, s[84:85]
	s_mov_b32 m0, s36
	s_nop 0
	global_load_lds_dwordx4 v[228:229], off
	s_waitcnt vmcnt(8)
	s_waitcnt lgkmcnt(0)
	s_barrier
	s_cbranch_vccnz .LBB0_80
	s_setprio 1
	v_mfma_f32_16x16x32_bf16 v[60:63], v[144:147], v[186:189], v[60:63]
	v_mfma_f32_16x16x32_bf16 v[56:59], v[152:155], v[186:189], v[56:59]
	v_mfma_f32_16x16x32_bf16 v[44:47], v[144:147], v[178:181], v[44:47]
	v_mfma_f32_16x16x32_bf16 v[40:43], v[152:155], v[178:181], v[40:43]
	v_mfma_f32_16x16x32_bf16 v[28:31], v[144:147], v[170:173], v[28:31]
	v_mfma_f32_16x16x32_bf16 v[24:27], v[152:155], v[170:173], v[24:27]
	v_mfma_f32_16x16x32_bf16 v[12:15], v[144:147], v[162:165], v[12:15]
	v_mfma_f32_16x16x32_bf16 v[8:11], v[152:155], v[162:165], v[8:11]
	v_mfma_f32_16x16x32_bf16 v[60:63], v[148:151], v[190:193], v[60:63]
	v_mfma_f32_16x16x32_bf16 v[56:59], v[156:159], v[190:193], v[56:59]
	v_mfma_f32_16x16x32_bf16 v[44:47], v[148:151], v[182:185], v[44:47]
	v_mfma_f32_16x16x32_bf16 v[40:43], v[156:159], v[182:185], v[40:43]
	v_mfma_f32_16x16x32_bf16 v[28:31], v[148:151], v[174:177], v[28:31]
	v_mfma_f32_16x16x32_bf16 v[24:27], v[156:159], v[174:177], v[24:27]
	v_mfma_f32_16x16x32_bf16 v[12:15], v[148:151], v[166:169], v[12:15]
	v_mfma_f32_16x16x32_bf16 v[8:11], v[156:159], v[166:169], v[8:11]
	s_setprio 0
	s_setprio 1
	v_mfma_f32_16x16x32_bf16 v[52:55], v[128:131], v[186:189], v[52:55]
	v_mfma_f32_16x16x32_bf16 v[48:51], v[136:139], v[186:189], v[48:51]
	v_mfma_f32_16x16x32_bf16 v[36:39], v[128:131], v[178:181], v[36:39]
	v_mfma_f32_16x16x32_bf16 v[32:35], v[136:139], v[178:181], v[32:35]
	v_mfma_f32_16x16x32_bf16 v[20:23], v[128:131], v[170:173], v[20:23]
	v_mfma_f32_16x16x32_bf16 v[16:19], v[136:139], v[170:173], v[16:19]
	v_mfma_f32_16x16x32_bf16 v[4:7], v[128:131], v[162:165], v[4:7]
	v_mfma_f32_16x16x32_bf16 v[0:3], v[136:139], v[162:165], v[0:3]
	v_mfma_f32_16x16x32_bf16 v[52:55], v[132:135], v[190:193], v[52:55]
	v_mfma_f32_16x16x32_bf16 v[48:51], v[140:143], v[190:193], v[48:51]
	v_mfma_f32_16x16x32_bf16 v[36:39], v[132:135], v[182:185], v[36:39]
	v_mfma_f32_16x16x32_bf16 v[32:35], v[140:143], v[182:185], v[32:35]
	v_mfma_f32_16x16x32_bf16 v[20:23], v[132:135], v[174:177], v[20:23]
	v_mfma_f32_16x16x32_bf16 v[16:19], v[140:143], v[174:177], v[16:19]
	v_mfma_f32_16x16x32_bf16 v[4:7], v[132:135], v[166:169], v[4:7]
	v_mfma_f32_16x16x32_bf16 v[0:3], v[140:143], v[166:169], v[0:3]
	s_setprio 0
	s_branch .LBB0_80

.LBB0_187:
	s_add_u32 s42, s8, 0x80
	s_addc_u32 s43, s9, 0
	s_add_i32 s46, 16, 0x10000
	s_cmp_eq_u32 s21, s5
	s_cselect_b64 s[44:45], -1, 0
	s_and_b64 s[10:11], s[44:45], exec
	s_cselect_b32 s43, s1, s43
	s_cselect_b32 s42, s17, s42
	s_cselect_b32 s11, s13, s96
	s_cselect_b32 s10, s20, s35
	s_add_i32 s54, 16, 0x14000
	v_add_u32_e32 v128, s46, v222
	v_add_u32_e32 v140, s54, v222
	ds_read_b128 v[144:147], v128
	ds_read_b128 v[148:151], v128 offset:1024
	ds_read_b128 v[152:155], v128 offset:2048
	ds_read_b128 v[156:159], v128 offset:3072
	ds_read_b128 v[128:131], v140
	ds_read_b128 v[132:135], v140 offset:1024
	ds_read_b128 v[136:139], v140 offset:2048
	ds_read_b128 v[140:143], v140 offset:3072
	v_lshl_add_u64 v[202:203], s[8:9], 0, v[212:213]
	s_add_i32 m0, s29, 0xc000
	s_waitcnt lgkmcnt(0)
	ds_read_b128 v[162:165], v224
	ds_read_b128 v[166:169], v224 offset:1024
	ds_read_b128 v[170:173], v224 offset:2048
	ds_read_b128 v[174:177], v224 offset:3072
	ds_read_b128 v[178:181], v224 offset:4096
	ds_read_b128 v[182:185], v224 offset:5120
	ds_read_b128 v[186:189], v224 offset:6144
	ds_read_b128 v[190:193], v224 offset:7168
	global_load_lds_dwordx4 v[202:203], off
	v_lshl_add_u64 v[202:203], s[8:9], 0, v[210:211]
	s_add_i32 m0, s29, 0xe000
	s_nop 0
	global_load_lds_dwordx4 v[202:203], off
	s_waitcnt vmcnt(8)
	s_waitcnt lgkmcnt(0)
	s_barrier
	s_setprio 1
	v_mfma_f32_16x16x32_bf16 v[124:127], v[144:147], v[162:165], v[124:127]
	v_mfma_f32_16x16x32_bf16 v[120:123], v[152:155], v[162:165], v[120:123]
	v_mfma_f32_16x16x32_bf16 v[116:119], v[144:147], v[170:173], v[116:119]
	v_mfma_f32_16x16x32_bf16 v[112:115], v[152:155], v[170:173], v[112:115]
	v_mfma_f32_16x16x32_bf16 v[108:111], v[144:147], v[178:181], v[108:111]
	v_mfma_f32_16x16x32_bf16 v[104:107], v[152:155], v[178:181], v[104:107]
	v_mfma_f32_16x16x32_bf16 v[100:103], v[144:147], v[186:189], v[100:103]
	v_mfma_f32_16x16x32_bf16 v[96:99], v[152:155], v[186:189], v[96:99]
	v_mfma_f32_16x16x32_bf16 v[124:127], v[148:151], v[166:169], v[124:127]
	v_mfma_f32_16x16x32_bf16 v[120:123], v[156:159], v[166:169], v[120:123]
	v_mfma_f32_16x16x32_bf16 v[116:119], v[148:151], v[174:177], v[116:119]
	v_mfma_f32_16x16x32_bf16 v[112:115], v[156:159], v[174:177], v[112:115]
	v_mfma_f32_16x16x32_bf16 v[108:111], v[148:151], v[182:185], v[108:111]
	v_mfma_f32_16x16x32_bf16 v[104:107], v[156:159], v[182:185], v[104:107]
	v_mfma_f32_16x16x32_bf16 v[100:103], v[148:151], v[190:193], v[100:103]
	v_mfma_f32_16x16x32_bf16 v[96:99], v[156:159], v[190:193], v[96:99]
	s_setprio 0
	s_setprio 1
	v_mfma_f32_16x16x32_bf16 v[92:95], v[128:131], v[162:165], v[92:95]
	v_mfma_f32_16x16x32_bf16 v[88:91], v[136:139], v[162:165], v[88:91]
	v_mfma_f32_16x16x32_bf16 v[84:87], v[128:131], v[170:173], v[84:87]
	v_mfma_f32_16x16x32_bf16 v[80:83], v[136:139], v[170:173], v[80:83]
	v_mfma_f32_16x16x32_bf16 v[76:79], v[128:131], v[178:181], v[76:79]
	v_mfma_f32_16x16x32_bf16 v[72:75], v[136:139], v[178:181], v[72:75]
	v_mfma_f32_16x16x32_bf16 v[68:71], v[128:131], v[186:189], v[68:71]
	v_mfma_f32_16x16x32_bf16 v[64:67], v[136:139], v[186:189], v[64:67]
	v_mfma_f32_16x16x32_bf16 v[92:95], v[132:135], v[166:169], v[92:95]
	v_mfma_f32_16x16x32_bf16 v[88:91], v[140:143], v[166:169], v[88:91]
	v_mfma_f32_16x16x32_bf16 v[84:87], v[132:135], v[174:177], v[84:87]
	v_mfma_f32_16x16x32_bf16 v[80:83], v[140:143], v[174:177], v[80:83]
	v_mfma_f32_16x16x32_bf16 v[76:79], v[132:135], v[182:185], v[76:79]
	v_mfma_f32_16x16x32_bf16 v[72:75], v[140:143], v[182:185], v[72:75]
	v_mfma_f32_16x16x32_bf16 v[68:71], v[132:135], v[190:193], v[68:71]
	v_mfma_f32_16x16x32_bf16 v[64:67], v[140:143], v[190:193], v[64:67]
	s_setprio 0
	s_barrier
	s_add_i32 s46, s46, s14
	v_lshl_add_u64 v[214:215], s[10:11], 0, v[196:197]
	s_mov_b32 m0, s46
	ds_read_b128 v[186:189], v224 offset:16384
	ds_read_b128 v[190:193], v224 offset:17408
	ds_read_b128 v[178:181], v224 offset:18432
	ds_read_b128 v[182:185], v224 offset:19456
	ds_read_b128 v[170:173], v224 offset:20480
	ds_read_b128 v[174:177], v224 offset:21504
	ds_read_b128 v[162:165], v224 offset:22528
	ds_read_b128 v[166:169], v224 offset:23552
	global_load_lds_dwordx4 v[214:215], off
	s_add_i32 m0, s46, 0x2000
	s_add_u32 s46, s10, 0x40000
	v_lshl_add_u64 v[216:217], s[10:11], 0, v[200:201]
	s_addc_u32 s47, s11, 0
	s_add_i32 s54, s54, s14
	global_load_lds_dwordx4 v[216:217], off
	v_lshl_add_u64 v[202:203], s[46:47], 0, v[196:197]
	s_mov_b32 m0, s54
	v_lshl_add_u64 v[218:219], s[42:43], 0, v[194:195]
	global_load_lds_dwordx4 v[202:203], off
	v_lshl_add_u64 v[202:203], s[46:47], 0, v[200:201]
	s_add_i32 m0, s54, 0x2000
	v_lshl_add_u64 v[220:221], s[42:43], 0, v[198:199]
	global_load_lds_dwordx4 v[202:203], off
	s_mov_b32 m0, s29
	v_cndmask_b32_e64 v160, 0, 1, s[6:7]
	global_load_lds_dwordx4 v[218:219], off
	s_mov_b32 m0, s15
	v_cmp_ne_u32_e64 s[46:47], 1, v160
	global_load_lds_dwordx4 v[220:221], off
	s_waitcnt vmcnt(8)
	s_waitcnt lgkmcnt(0)
	s_andn2_b64 vcc, exec, s[6:7]
	s_barrier
	s_cbranch_vccnz .LBB0_189
	s_setprio 1
	v_mfma_f32_16x16x32_bf16 v[60:63], v[144:147], v[186:189], v[60:63]
	v_mfma_f32_16x16x32_bf16 v[56:59], v[152:155], v[186:189], v[56:59]
	v_mfma_f32_16x16x32_bf16 v[52:55], v[144:147], v[178:181], v[52:55]
	v_mfma_f32_16x16x32_bf16 v[48:51], v[152:155], v[178:181], v[48:51]
	v_mfma_f32_16x16x32_bf16 v[44:47], v[144:147], v[170:173], v[44:47]
	v_mfma_f32_16x16x32_bf16 v[40:43], v[152:155], v[170:173], v[40:43]
	v_mfma_f32_16x16x32_bf16 v[36:39], v[144:147], v[162:165], v[36:39]
	v_mfma_f32_16x16x32_bf16 v[32:35], v[152:155], v[162:165], v[32:35]
	v_mfma_f32_16x16x32_bf16 v[60:63], v[148:151], v[190:193], v[60:63]
	v_mfma_f32_16x16x32_bf16 v[56:59], v[156:159], v[190:193], v[56:59]
	v_mfma_f32_16x16x32_bf16 v[52:55], v[148:151], v[182:185], v[52:55]
	v_mfma_f32_16x16x32_bf16 v[48:51], v[156:159], v[182:185], v[48:51]
	v_mfma_f32_16x16x32_bf16 v[44:47], v[148:151], v[174:177], v[44:47]
	v_mfma_f32_16x16x32_bf16 v[40:43], v[156:159], v[174:177], v[40:43]
	v_mfma_f32_16x16x32_bf16 v[36:39], v[148:151], v[166:169], v[36:39]
	v_mfma_f32_16x16x32_bf16 v[32:35], v[156:159], v[166:169], v[32:35]
	s_setprio 0
	s_setprio 1
	v_mfma_f32_16x16x32_bf16 v[28:31], v[128:131], v[186:189], v[28:31]
	v_mfma_f32_16x16x32_bf16 v[24:27], v[136:139], v[186:189], v[24:27]
	v_mfma_f32_16x16x32_bf16 v[20:23], v[128:131], v[178:181], v[20:23]
	v_mfma_f32_16x16x32_bf16 v[16:19], v[136:139], v[178:181], v[16:19]
	v_mfma_f32_16x16x32_bf16 v[12:15], v[128:131], v[170:173], v[12:15]
	v_mfma_f32_16x16x32_bf16 v[8:11], v[136:139], v[170:173], v[8:11]
	v_mfma_f32_16x16x32_bf16 v[4:7], v[128:131], v[162:165], v[4:7]
	v_mfma_f32_16x16x32_bf16 v[0:3], v[136:139], v[162:165], v[0:3]
	v_mfma_f32_16x16x32_bf16 v[28:31], v[132:135], v[190:193], v[28:31]
	v_mfma_f32_16x16x32_bf16 v[24:27], v[140:143], v[190:193], v[24:27]
	v_mfma_f32_16x16x32_bf16 v[20:23], v[132:135], v[182:185], v[20:23]
	v_mfma_f32_16x16x32_bf16 v[16:19], v[140:143], v[182:185], v[16:19]
	v_mfma_f32_16x16x32_bf16 v[12:15], v[132:135], v[174:177], v[12:15]
	v_mfma_f32_16x16x32_bf16 v[8:11], v[140:143], v[174:177], v[8:11]
	v_mfma_f32_16x16x32_bf16 v[4:7], v[132:135], v[166:169], v[4:7]
	v_mfma_f32_16x16x32_bf16 v[0:3], v[140:143], v[166:169], v[0:3]
	s_setprio 0
.LBB0_189:
	s_barrier
	s_add_i32 s54, 16, 0x18000
	s_add_i32 s55, 16, 0x1c000
	v_add_u32_e32 v128, s54, v222
	v_add_u32_e32 v140, s55, v222
	ds_read_b128 v[144:147], v128
	ds_read_b128 v[148:151], v128 offset:1024
	ds_read_b128 v[152:155], v128 offset:2048
	ds_read_b128 v[156:159], v128 offset:3072
	ds_read_b128 v[128:131], v140
	ds_read_b128 v[132:135], v140 offset:1024
	ds_read_b128 v[136:139], v140 offset:2048
	ds_read_b128 v[140:143], v140 offset:3072
	s_and_b64 s[44:45], s[40:41], s[44:45]
	s_and_b64 s[44:45], s[44:45], exec
	s_cselect_b32 s45, s12, s4
	s_cselect_b32 s44, 0, 0
	s_add_u32 s42, s42, s45
	s_addc_u32 s43, s43, s44
	s_mov_b32 m0, s38
	v_lshl_add_u64 v[202:203], s[42:43], 0, v[194:195]
	s_waitcnt lgkmcnt(0)
	ds_read_b128 v[162:165], v224 offset:32768
	ds_read_b128 v[166:169], v224 offset:33792
	ds_read_b128 v[170:173], v224 offset:34816
	ds_read_b128 v[174:177], v224 offset:35840
	ds_read_b128 v[178:181], v224 offset:36864
	ds_read_b128 v[182:185], v224 offset:37888
	ds_read_b128 v[186:189], v224 offset:38912
	ds_read_b128 v[190:193], v224 offset:39936
	global_load_lds_dwordx4 v[202:203], off
	v_lshl_add_u64 v[202:203], s[42:43], 0, v[198:199]
	s_mov_b32 m0, s39
	s_nop 0
	global_load_lds_dwordx4 v[202:203], off
	s_waitcnt vmcnt(8)
	s_waitcnt lgkmcnt(0)
	s_barrier
	s_setprio 1
	v_mfma_f32_16x16x32_bf16 v[124:127], v[144:147], v[162:165], v[124:127]
	v_mfma_f32_16x16x32_bf16 v[120:123], v[152:155], v[162:165], v[120:123]
	v_mfma_f32_16x16x32_bf16 v[116:119], v[144:147], v[170:173], v[116:119]
	v_mfma_f32_16x16x32_bf16 v[112:115], v[152:155], v[170:173], v[112:115]
	v_mfma_f32_16x16x32_bf16 v[108:111], v[144:147], v[178:181], v[108:111]
	v_mfma_f32_16x16x32_bf16 v[104:107], v[152:155], v[178:181], v[104:107]
	v_mfma_f32_16x16x32_bf16 v[100:103], v[144:147], v[186:189], v[100:103]
	v_mfma_f32_16x16x32_bf16 v[96:99], v[152:155], v[186:189], v[96:99]
	v_mfma_f32_16x16x32_bf16 v[124:127], v[148:151], v[166:169], v[124:127]
	v_mfma_f32_16x16x32_bf16 v[120:123], v[156:159], v[166:169], v[120:123]
	v_mfma_f32_16x16x32_bf16 v[116:119], v[148:151], v[174:177], v[116:119]
	v_mfma_f32_16x16x32_bf16 v[112:115], v[156:159], v[174:177], v[112:115]
	v_mfma_f32_16x16x32_bf16 v[108:111], v[148:151], v[182:185], v[108:111]
	v_mfma_f32_16x16x32_bf16 v[104:107], v[156:159], v[182:185], v[104:107]
	v_mfma_f32_16x16x32_bf16 v[100:103], v[148:151], v[190:193], v[100:103]
	v_mfma_f32_16x16x32_bf16 v[96:99], v[156:159], v[190:193], v[96:99]
	s_setprio 0
	s_setprio 1
	v_mfma_f32_16x16x32_bf16 v[92:95], v[128:131], v[162:165], v[92:95]
	v_mfma_f32_16x16x32_bf16 v[88:91], v[136:139], v[162:165], v[88:91]
	v_mfma_f32_16x16x32_bf16 v[84:87], v[128:131], v[170:173], v[84:87]
	v_mfma_f32_16x16x32_bf16 v[80:83], v[136:139], v[170:173], v[80:83]
	v_mfma_f32_16x16x32_bf16 v[76:79], v[128:131], v[178:181], v[76:79]
	v_mfma_f32_16x16x32_bf16 v[72:75], v[136:139], v[178:181], v[72:75]
	v_mfma_f32_16x16x32_bf16 v[68:71], v[128:131], v[186:189], v[68:71]
	v_mfma_f32_16x16x32_bf16 v[64:67], v[136:139], v[186:189], v[64:67]
	v_mfma_f32_16x16x32_bf16 v[92:95], v[132:135], v[166:169], v[92:95]
	v_mfma_f32_16x16x32_bf16 v[88:91], v[140:143], v[166:169], v[88:91]
	v_mfma_f32_16x16x32_bf16 v[84:87], v[132:135], v[174:177], v[84:87]
	v_mfma_f32_16x16x32_bf16 v[80:83], v[140:143], v[174:177], v[80:83]
	v_mfma_f32_16x16x32_bf16 v[76:79], v[132:135], v[182:185], v[76:79]
	v_mfma_f32_16x16x32_bf16 v[72:75], v[140:143], v[182:185], v[72:75]
	v_mfma_f32_16x16x32_bf16 v[68:71], v[132:135], v[190:193], v[68:71]
	v_mfma_f32_16x16x32_bf16 v[64:67], v[140:143], v[190:193], v[64:67]
	s_setprio 0
	s_barrier
	s_add_i32 s42, s54, s14
	v_lshl_add_u64 v[202:203], v[214:215], 0, s[84:85]
	s_mov_b32 m0, s42
	ds_read_b128 v[186:189], v224 offset:49152
	ds_read_b128 v[190:193], v224 offset:50176
	ds_read_b128 v[178:181], v224 offset:51200
	ds_read_b128 v[182:185], v224 offset:52224
	ds_read_b128 v[170:173], v224 offset:53248
	ds_read_b128 v[174:177], v224 offset:54272
	ds_read_b128 v[162:165], v224 offset:55296
	ds_read_b128 v[166:169], v224 offset:56320
	global_load_lds_dwordx4 v[202:203], off
	s_add_i32 m0, s42, 0x2000
	s_add_u32 s10, s10, 0x40080
	v_lshl_add_u64 v[202:203], v[216:217], 0, s[84:85]
	s_addc_u32 s11, s11, 0
	s_add_i32 s42, s55, s14
	global_load_lds_dwordx4 v[202:203], off
	v_lshl_add_u64 v[202:203], s[10:11], 0, v[196:197]
	s_mov_b32 m0, s42
	s_and_b64 vcc, exec, s[46:47]
	global_load_lds_dwordx4 v[202:203], off
	v_lshl_add_u64 v[202:203], s[10:11], 0, v[200:201]
	s_add_i32 m0, s42, 0x2000
	s_nop 0
	global_load_lds_dwordx4 v[202:203], off
	v_lshl_add_u64 v[202:203], v[218:219], 0, s[84:85]
	s_mov_b32 m0, s48
	s_nop 0
	global_load_lds_dwordx4 v[202:203], off
	v_lshl_add_u64 v[202:203], v[220:221], 0, s[84:85]
	s_mov_b32 m0, s49
	s_nop 0
	global_load_lds_dwordx4 v[202:203], off
	s_waitcnt vmcnt(8)
	s_waitcnt lgkmcnt(0)
	s_barrier
	s_cbranch_vccnz .LBB0_186
	s_setprio 1
	v_mfma_f32_16x16x32_bf16 v[60:63], v[144:147], v[186:189], v[60:63]
	v_mfma_f32_16x16x32_bf16 v[56:59], v[152:155], v[186:189], v[56:59]
	v_mfma_f32_16x16x32_bf16 v[52:55], v[144:147], v[178:181], v[52:55]
	v_mfma_f32_16x16x32_bf16 v[48:51], v[152:155], v[178:181], v[48:51]
	v_mfma_f32_16x16x32_bf16 v[44:47], v[144:147], v[170:173], v[44:47]
	v_mfma_f32_16x16x32_bf16 v[40:43], v[152:155], v[170:173], v[40:43]
	v_mfma_f32_16x16x32_bf16 v[36:39], v[144:147], v[162:165], v[36:39]
	v_mfma_f32_16x16x32_bf16 v[32:35], v[152:155], v[162:165], v[32:35]
	v_mfma_f32_16x16x32_bf16 v[60:63], v[148:151], v[190:193], v[60:63]
	v_mfma_f32_16x16x32_bf16 v[56:59], v[156:159], v[190:193], v[56:59]
	v_mfma_f32_16x16x32_bf16 v[52:55], v[148:151], v[182:185], v[52:55]
	v_mfma_f32_16x16x32_bf16 v[48:51], v[156:159], v[182:185], v[48:51]
	v_mfma_f32_16x16x32_bf16 v[44:47], v[148:151], v[174:177], v[44:47]
	v_mfma_f32_16x16x32_bf16 v[40:43], v[156:159], v[174:177], v[40:43]
	v_mfma_f32_16x16x32_bf16 v[36:39], v[148:151], v[166:169], v[36:39]
	v_mfma_f32_16x16x32_bf16 v[32:35], v[156:159], v[166:169], v[32:35]
	s_setprio 0
	s_setprio 1
	v_mfma_f32_16x16x32_bf16 v[28:31], v[128:131], v[186:189], v[28:31]
	v_mfma_f32_16x16x32_bf16 v[24:27], v[136:139], v[186:189], v[24:27]
	v_mfma_f32_16x16x32_bf16 v[20:23], v[128:131], v[178:181], v[20:23]
	v_mfma_f32_16x16x32_bf16 v[16:19], v[136:139], v[178:181], v[16:19]
	v_mfma_f32_16x16x32_bf16 v[12:15], v[128:131], v[170:173], v[12:15]
	v_mfma_f32_16x16x32_bf16 v[8:11], v[136:139], v[170:173], v[8:11]
	v_mfma_f32_16x16x32_bf16 v[4:7], v[128:131], v[162:165], v[4:7]
	v_mfma_f32_16x16x32_bf16 v[0:3], v[136:139], v[162:165], v[0:3]
	v_mfma_f32_16x16x32_bf16 v[28:31], v[132:135], v[190:193], v[28:31]
	v_mfma_f32_16x16x32_bf16 v[24:27], v[140:143], v[190:193], v[24:27]
	v_mfma_f32_16x16x32_bf16 v[20:23], v[132:135], v[182:185], v[20:23]
	v_mfma_f32_16x16x32_bf16 v[16:19], v[140:143], v[182:185], v[16:19]
	v_mfma_f32_16x16x32_bf16 v[12:15], v[132:135], v[174:177], v[12:15]
	v_mfma_f32_16x16x32_bf16 v[8:11], v[140:143], v[174:177], v[8:11]
	v_mfma_f32_16x16x32_bf16 v[4:7], v[132:135], v[166:169], v[4:7]
	v_mfma_f32_16x16x32_bf16 v[0:3], v[140:143], v[166:169], v[0:3]
	s_setprio 0
	s_branch .LBB0_186

.LBB0_586:
	s_add_u32 s10, s4, s8
	s_addc_u32 s11, s5, s9
	s_add_u32 s28, s10, 0x100
	s_addc_u32 s29, s11, 0
	s_add_u32 s40, s13, s8
	s_addc_u32 s41, s37, s9
	s_add_i32 s55, 16, 0x10000
	s_cmpk_eq_i32 s8, 0x1500
	s_cselect_b64 s[30:31], -1, 0
	s_and_b64 s[10:11], s[30:31], exec
	s_cselect_b32 s29, s17, s29
	s_cselect_b32 s28, s16, s28
	s_waitcnt lgkmcnt(0)
	v_add_u32_e32 v96, s55, v203
	s_cselect_b32 s11, s19, s41
	s_cselect_b32 s10, s18, s40
	s_add_i32 s96, 16, 0x14000
	ds_read_b128 v[162:165], v96
	ds_read_b128 v[166:169], v96 offset:1024
	ds_read_b128 v[170:173], v96 offset:2048
	ds_read_b128 v[174:177], v96 offset:3072
	v_add_u32_e32 v96, s96, v203
	ds_read_b128 v[144:147], v96
	ds_read_b128 v[148:151], v96 offset:1024
	ds_read_b128 v[152:155], v96 offset:2048
	ds_read_b128 v[156:159], v96 offset:3072
	v_lshl_add_u64 v[96:97], v[208:209], 0, s[8:9]
	s_add_i32 m0, s15, 0xc000
	ds_read_b128 v[178:181], v218
	ds_read_b128 v[182:185], v218 offset:1024
	ds_read_b128 v[186:189], v218 offset:2048
	ds_read_b128 v[190:193], v218 offset:3072
	ds_read_b128 v[210:213], v218 offset:4096
	ds_read_b128 v[214:217], v218 offset:5120
	ds_read_b128 v[220:223], v218 offset:6144
	ds_read_b128 v[224:227], v218 offset:7168
	global_load_lds_dwordx4 v[96:97], off
	v_lshl_add_u64 v[96:97], v[206:207], 0, s[8:9]
	s_add_i32 m0, s15, 0xe000
	s_nop 0
	global_load_lds_dwordx4 v[96:97], off
	s_waitcnt vmcnt(8)
	s_waitcnt lgkmcnt(0)
	s_barrier
	s_setprio 1
	v_mfma_f32_16x16x32_bf16 v[96:99], v[162:165], v[178:181], v[140:143]
	v_mfma_f32_16x16x32_bf16 v[100:103], v[170:173], v[178:181], v[136:139]
	v_mfma_f32_16x16x32_bf16 v[104:107], v[162:165], v[186:189], v[124:127]
	v_mfma_f32_16x16x32_bf16 v[108:111], v[170:173], v[186:189], v[120:123]
	v_mfma_f32_16x16x32_bf16 v[92:95], v[162:165], v[210:213], v[92:95]
	v_mfma_f32_16x16x32_bf16 v[88:91], v[170:173], v[210:213], v[88:91]
	v_mfma_f32_16x16x32_bf16 v[76:79], v[162:165], v[220:223], v[76:79]
	v_mfma_f32_16x16x32_bf16 v[72:75], v[170:173], v[220:223], v[72:75]
	v_mfma_f32_16x16x32_bf16 v[96:99], v[166:169], v[182:185], v[96:99]
	v_mfma_f32_16x16x32_bf16 v[100:103], v[174:177], v[182:185], v[100:103]
	v_mfma_f32_16x16x32_bf16 v[104:107], v[166:169], v[190:193], v[104:107]
	v_mfma_f32_16x16x32_bf16 v[108:111], v[174:177], v[190:193], v[108:111]
	v_mfma_f32_16x16x32_bf16 v[92:95], v[166:169], v[214:217], v[92:95]
	v_mfma_f32_16x16x32_bf16 v[88:91], v[174:177], v[214:217], v[88:91]
	v_mfma_f32_16x16x32_bf16 v[76:79], v[166:169], v[224:227], v[76:79]
	v_mfma_f32_16x16x32_bf16 v[72:75], v[174:177], v[224:227], v[72:75]
	s_setprio 0
	s_setprio 1
	v_mfma_f32_16x16x32_bf16 v[120:123], v[144:147], v[178:181], v[132:135]
	v_mfma_f32_16x16x32_bf16 v[132:135], v[148:151], v[182:185], v[120:123]
	v_mfma_f32_16x16x32_bf16 v[120:123], v[152:155], v[178:181], v[128:131]
	v_mfma_f32_16x16x32_bf16 v[116:119], v[144:147], v[186:189], v[116:119]
	v_mfma_f32_16x16x32_bf16 v[112:115], v[152:155], v[186:189], v[112:115]
	v_mfma_f32_16x16x32_bf16 v[84:87], v[144:147], v[210:213], v[84:87]
	v_mfma_f32_16x16x32_bf16 v[80:83], v[152:155], v[210:213], v[80:83]
	v_mfma_f32_16x16x32_bf16 v[68:71], v[144:147], v[220:223], v[68:71]
	v_mfma_f32_16x16x32_bf16 v[64:67], v[152:155], v[220:223], v[64:67]
	v_mfma_f32_16x16x32_bf16 v[128:131], v[156:159], v[182:185], v[120:123]
	v_mfma_f32_16x16x32_bf16 v[116:119], v[148:151], v[190:193], v[116:119]
	v_mfma_f32_16x16x32_bf16 v[112:115], v[156:159], v[190:193], v[112:115]
	v_mfma_f32_16x16x32_bf16 v[84:87], v[148:151], v[214:217], v[84:87]
	v_mfma_f32_16x16x32_bf16 v[80:83], v[156:159], v[214:217], v[80:83]
	v_mfma_f32_16x16x32_bf16 v[68:71], v[148:151], v[224:227], v[68:71]
	v_mfma_f32_16x16x32_bf16 v[64:67], v[156:159], v[224:227], v[64:67]
	s_setprio 0
	s_barrier
	s_add_i32 s40, s55, s14
	v_lshl_add_u64 v[210:211], s[10:11], 0, v[194:195]
	s_mov_b32 m0, s40
	ds_read_b128 v[186:189], v218 offset:16384
	ds_read_b128 v[190:193], v218 offset:17408
	ds_read_b128 v[178:181], v218 offset:18432
	ds_read_b128 v[182:185], v218 offset:19456
	ds_read_b128 v[136:139], v218 offset:20480
	ds_read_b128 v[140:143], v218 offset:21504
	ds_read_b128 v[120:123], v218 offset:22528
	ds_read_b128 v[124:127], v218 offset:23552
	global_load_lds_dwordx4 v[210:211], off
	s_add_i32 m0, s40, 0x2000
	s_add_u32 s40, s10, 0xb0000
	v_lshl_add_u64 v[212:213], s[10:11], 0, v[196:197]
	s_addc_u32 s41, s11, 0
	s_add_i32 s55, s96, s14
	global_load_lds_dwordx4 v[212:213], off
	v_lshl_add_u64 v[214:215], s[40:41], 0, v[194:195]
	s_mov_b32 m0, s55
	v_lshl_add_u64 v[216:217], s[28:29], 0, v[196:197]
	global_load_lds_dwordx4 v[214:215], off
	v_lshl_add_u64 v[214:215], s[40:41], 0, v[196:197]
	s_add_i32 m0, s55, 0x2000
	v_cndmask_b32_e64 v160, 0, 1, s[6:7]
	global_load_lds_dwordx4 v[214:215], off
	v_lshl_add_u64 v[214:215], s[28:29], 0, v[194:195]
	s_mov_b32 m0, s15
	v_cmp_ne_u32_e64 s[40:41], 1, v160
	global_load_lds_dwordx4 v[214:215], off
	s_mov_b32 m0, s20
	s_andn2_b64 vcc, exec, s[6:7]
	global_load_lds_dwordx4 v[216:217], off
	s_waitcnt vmcnt(8)
	s_waitcnt lgkmcnt(0)
	s_barrier
	s_cbranch_vccnz .LBB0_588
	s_setprio 1
	v_mfma_f32_16x16x32_bf16 v[60:63], v[162:165], v[186:189], v[60:63]
	v_mfma_f32_16x16x32_bf16 v[56:59], v[170:173], v[186:189], v[56:59]
	v_mfma_f32_16x16x32_bf16 v[44:47], v[162:165], v[178:181], v[44:47]
	v_mfma_f32_16x16x32_bf16 v[40:43], v[170:173], v[178:181], v[40:43]
	v_mfma_f32_16x16x32_bf16 v[28:31], v[162:165], v[136:139], v[28:31]
	v_mfma_f32_16x16x32_bf16 v[24:27], v[170:173], v[136:139], v[24:27]
	v_mfma_f32_16x16x32_bf16 v[12:15], v[162:165], v[120:123], v[12:15]
	v_mfma_f32_16x16x32_bf16 v[8:11], v[170:173], v[120:123], v[8:11]
	v_mfma_f32_16x16x32_bf16 v[60:63], v[166:169], v[190:193], v[60:63]
	v_mfma_f32_16x16x32_bf16 v[56:59], v[174:177], v[190:193], v[56:59]
	v_mfma_f32_16x16x32_bf16 v[44:47], v[166:169], v[182:185], v[44:47]
	v_mfma_f32_16x16x32_bf16 v[40:43], v[174:177], v[182:185], v[40:43]
	v_mfma_f32_16x16x32_bf16 v[28:31], v[166:169], v[140:143], v[28:31]
	v_mfma_f32_16x16x32_bf16 v[24:27], v[174:177], v[140:143], v[24:27]
	v_mfma_f32_16x16x32_bf16 v[12:15], v[166:169], v[124:127], v[12:15]
	v_mfma_f32_16x16x32_bf16 v[8:11], v[174:177], v[124:127], v[8:11]
	s_setprio 0
	s_setprio 1
	v_mfma_f32_16x16x32_bf16 v[52:55], v[144:147], v[186:189], v[52:55]
	v_mfma_f32_16x16x32_bf16 v[48:51], v[152:155], v[186:189], v[48:51]
	v_mfma_f32_16x16x32_bf16 v[36:39], v[144:147], v[178:181], v[36:39]
	v_mfma_f32_16x16x32_bf16 v[32:35], v[152:155], v[178:181], v[32:35]
	v_mfma_f32_16x16x32_bf16 v[20:23], v[144:147], v[136:139], v[20:23]
	v_mfma_f32_16x16x32_bf16 v[16:19], v[152:155], v[136:139], v[16:19]
	v_mfma_f32_16x16x32_bf16 v[4:7], v[144:147], v[120:123], v[4:7]
	v_mfma_f32_16x16x32_bf16 v[0:3], v[152:155], v[120:123], v[0:3]
	v_mfma_f32_16x16x32_bf16 v[52:55], v[148:151], v[190:193], v[52:55]
	v_mfma_f32_16x16x32_bf16 v[48:51], v[156:159], v[190:193], v[48:51]
	v_mfma_f32_16x16x32_bf16 v[36:39], v[148:151], v[182:185], v[36:39]
	v_mfma_f32_16x16x32_bf16 v[32:35], v[156:159], v[182:185], v[32:35]
	v_mfma_f32_16x16x32_bf16 v[20:23], v[148:151], v[140:143], v[20:23]
	v_mfma_f32_16x16x32_bf16 v[16:19], v[156:159], v[140:143], v[16:19]
	v_mfma_f32_16x16x32_bf16 v[4:7], v[148:151], v[124:127], v[4:7]
	v_mfma_f32_16x16x32_bf16 v[0:3], v[156:159], v[124:127], v[0:3]
	s_setprio 0
.LBB0_588:
	s_barrier
	s_add_i32 s55, 16, 0x18000
	s_waitcnt lgkmcnt(0)
	v_add_u32_e32 v120, s55, v203
	s_add_i32 s96, 16, 0x1c000
	ds_read_b128 v[162:165], v120
	ds_read_b128 v[166:169], v120 offset:1024
	ds_read_b128 v[170:173], v120 offset:2048
	ds_read_b128 v[174:177], v120 offset:3072
	v_add_u32_e32 v120, s96, v203
	ds_read_b128 v[144:147], v120
	ds_read_b128 v[148:151], v120 offset:1024
	ds_read_b128 v[152:155], v120 offset:2048
	ds_read_b128 v[156:159], v120 offset:3072
	s_and_b64 s[30:31], s[42:43], s[30:31]
	s_and_b64 s[30:31], s[30:31], exec
	s_cselect_b32 s31, s12, s64
	s_cselect_b32 s30, 0, 0
	s_add_u32 s28, s28, s31
	s_addc_u32 s29, s29, s30
	s_mov_b32 m0, s21
	v_lshl_add_u64 v[120:121], s[28:29], 0, v[194:195]
	ds_read_b128 v[178:181], v218 offset:32768
	ds_read_b128 v[182:185], v218 offset:33792
	ds_read_b128 v[186:189], v218 offset:34816
	ds_read_b128 v[190:193], v218 offset:35840
	ds_read_b128 v[220:223], v218 offset:36864
	ds_read_b128 v[224:227], v218 offset:37888
	ds_read_b128 v[228:231], v218 offset:38912
	ds_read_b128 v[232:235], v218 offset:39936
	global_load_lds_dwordx4 v[120:121], off
	v_lshl_add_u64 v[120:121], s[28:29], 0, v[196:197]
	s_mov_b32 m0, s34
	s_nop 0
	global_load_lds_dwordx4 v[120:121], off
	s_waitcnt vmcnt(8)
	s_waitcnt lgkmcnt(0)
	s_barrier
	s_setprio 1
	v_mfma_f32_16x16x32_bf16 v[96:99], v[162:165], v[178:181], v[96:99]
	v_mfma_f32_16x16x32_bf16 v[140:143], v[166:169], v[182:185], v[96:99]
	v_mfma_f32_16x16x32_bf16 v[96:99], v[170:173], v[178:181], v[100:103]
	v_mfma_f32_16x16x32_bf16 v[136:139], v[174:177], v[182:185], v[96:99]
	v_mfma_f32_16x16x32_bf16 v[96:99], v[162:165], v[186:189], v[104:107]
	v_mfma_f32_16x16x32_bf16 v[124:127], v[166:169], v[190:193], v[96:99]
	v_mfma_f32_16x16x32_bf16 v[96:99], v[170:173], v[186:189], v[108:111]
	v_mfma_f32_16x16x32_bf16 v[92:95], v[162:165], v[220:223], v[92:95]
	v_mfma_f32_16x16x32_bf16 v[88:91], v[170:173], v[220:223], v[88:91]
	v_mfma_f32_16x16x32_bf16 v[76:79], v[162:165], v[228:231], v[76:79]
	v_mfma_f32_16x16x32_bf16 v[72:75], v[170:173], v[228:231], v[72:75]
	v_mfma_f32_16x16x32_bf16 v[120:123], v[174:177], v[190:193], v[96:99]
	v_mfma_f32_16x16x32_bf16 v[92:95], v[166:169], v[224:227], v[92:95]
	v_mfma_f32_16x16x32_bf16 v[88:91], v[174:177], v[224:227], v[88:91]
	v_mfma_f32_16x16x32_bf16 v[76:79], v[166:169], v[232:235], v[76:79]
	v_mfma_f32_16x16x32_bf16 v[72:75], v[174:177], v[232:235], v[72:75]
	s_setprio 0
	s_setprio 1
	v_mfma_f32_16x16x32_bf16 v[96:99], v[144:147], v[178:181], v[132:135]
	v_mfma_f32_16x16x32_bf16 v[132:135], v[148:151], v[182:185], v[96:99]
	v_mfma_f32_16x16x32_bf16 v[96:99], v[152:155], v[178:181], v[128:131]
	v_mfma_f32_16x16x32_bf16 v[128:131], v[156:159], v[182:185], v[96:99]
	v_mfma_f32_16x16x32_bf16 v[96:99], v[144:147], v[186:189], v[116:119]
	v_mfma_f32_16x16x32_bf16 v[116:119], v[148:151], v[190:193], v[96:99]
	v_mfma_f32_16x16x32_bf16 v[96:99], v[152:155], v[186:189], v[112:115]
	v_mfma_f32_16x16x32_bf16 v[84:87], v[144:147], v[220:223], v[84:87]
	v_mfma_f32_16x16x32_bf16 v[80:83], v[152:155], v[220:223], v[80:83]
	v_mfma_f32_16x16x32_bf16 v[68:71], v[144:147], v[228:231], v[68:71]
	v_mfma_f32_16x16x32_bf16 v[64:67], v[152:155], v[228:231], v[64:67]
	v_mfma_f32_16x16x32_bf16 v[112:115], v[156:159], v[190:193], v[96:99]
	v_mfma_f32_16x16x32_bf16 v[84:87], v[148:151], v[224:227], v[84:87]
	v_mfma_f32_16x16x32_bf16 v[80:83], v[156:159], v[224:227], v[80:83]
	v_mfma_f32_16x16x32_bf16 v[68:71], v[148:151], v[232:235], v[68:71]
	v_mfma_f32_16x16x32_bf16 v[64:67], v[156:159], v[232:235], v[64:67]
	s_setprio 0
	s_barrier
	s_add_i32 s28, s55, s14
	v_lshl_add_u64 v[210:211], v[210:211], 0, s[84:85]
	s_mov_b32 m0, s28
	ds_read_b128 v[186:189], v218 offset:49152
	ds_read_b128 v[190:193], v218 offset:50176
	ds_read_b128 v[178:181], v218 offset:51200
	ds_read_b128 v[182:185], v218 offset:52224
	ds_read_b128 v[104:107], v218 offset:53248
	ds_read_b128 v[108:111], v218 offset:54272
	ds_read_b128 v[96:99], v218 offset:55296
	ds_read_b128 v[100:103], v218 offset:56320
	global_load_lds_dwordx4 v[210:211], off
	s_add_i32 m0, s28, 0x2000
	s_add_u32 s10, s10, 0xb0080
	v_lshl_add_u64 v[210:211], v[212:213], 0, s[84:85]
	s_addc_u32 s11, s11, 0
	s_add_i32 s28, s96, s14
	global_load_lds_dwordx4 v[210:211], off
	v_lshl_add_u64 v[210:211], s[10:11], 0, v[194:195]
	s_mov_b32 m0, s28
	s_and_b64 vcc, exec, s[40:41]
	global_load_lds_dwordx4 v[210:211], off
	v_lshl_add_u64 v[210:211], s[10:11], 0, v[196:197]
	s_add_i32 m0, s28, 0x2000
	s_nop 0
	global_load_lds_dwordx4 v[210:211], off
	v_lshl_add_u64 v[210:211], v[214:215], 0, s[84:85]
	s_mov_b32 m0, s45
	s_nop 0
	global_load_lds_dwordx4 v[210:211], off
	v_lshl_add_u64 v[210:211], v[216:217], 0, s[84:85]
	s_mov_b32 m0, s46
	s_nop 0
	global_load_lds_dwordx4 v[210:211], off
	s_waitcnt vmcnt(8)
	s_waitcnt lgkmcnt(0)
	s_barrier
	s_cbranch_vccnz .LBB0_585
	s_setprio 1
	v_mfma_f32_16x16x32_bf16 v[60:63], v[162:165], v[186:189], v[60:63]
	v_mfma_f32_16x16x32_bf16 v[56:59], v[170:173], v[186:189], v[56:59]
	v_mfma_f32_16x16x32_bf16 v[44:47], v[162:165], v[178:181], v[44:47]
	v_mfma_f32_16x16x32_bf16 v[40:43], v[170:173], v[178:181], v[40:43]
	v_mfma_f32_16x16x32_bf16 v[28:31], v[162:165], v[104:107], v[28:31]
	v_mfma_f32_16x16x32_bf16 v[24:27], v[170:173], v[104:107], v[24:27]
	v_mfma_f32_16x16x32_bf16 v[12:15], v[162:165], v[96:99], v[12:15]
	v_mfma_f32_16x16x32_bf16 v[8:11], v[170:173], v[96:99], v[8:11]
	v_mfma_f32_16x16x32_bf16 v[60:63], v[166:169], v[190:193], v[60:63]
	v_mfma_f32_16x16x32_bf16 v[56:59], v[174:177], v[190:193], v[56:59]
	v_mfma_f32_16x16x32_bf16 v[44:47], v[166:169], v[182:185], v[44:47]
	v_mfma_f32_16x16x32_bf16 v[40:43], v[174:177], v[182:185], v[40:43]
	v_mfma_f32_16x16x32_bf16 v[28:31], v[166:169], v[108:111], v[28:31]
	v_mfma_f32_16x16x32_bf16 v[24:27], v[174:177], v[108:111], v[24:27]
	v_mfma_f32_16x16x32_bf16 v[12:15], v[166:169], v[100:103], v[12:15]
	v_mfma_f32_16x16x32_bf16 v[8:11], v[174:177], v[100:103], v[8:11]
	s_setprio 0
	s_setprio 1
	v_mfma_f32_16x16x32_bf16 v[52:55], v[144:147], v[186:189], v[52:55]
	v_mfma_f32_16x16x32_bf16 v[48:51], v[152:155], v[186:189], v[48:51]
	v_mfma_f32_16x16x32_bf16 v[36:39], v[144:147], v[178:181], v[36:39]
	v_mfma_f32_16x16x32_bf16 v[32:35], v[152:155], v[178:181], v[32:35]
	v_mfma_f32_16x16x32_bf16 v[20:23], v[144:147], v[104:107], v[20:23]
	v_mfma_f32_16x16x32_bf16 v[16:19], v[152:155], v[104:107], v[16:19]
	v_mfma_f32_16x16x32_bf16 v[4:7], v[144:147], v[96:99], v[4:7]
	v_mfma_f32_16x16x32_bf16 v[0:3], v[152:155], v[96:99], v[0:3]
	v_mfma_f32_16x16x32_bf16 v[52:55], v[148:151], v[190:193], v[52:55]
	v_mfma_f32_16x16x32_bf16 v[48:51], v[156:159], v[190:193], v[48:51]
	v_mfma_f32_16x16x32_bf16 v[36:39], v[148:151], v[182:185], v[36:39]
	v_mfma_f32_16x16x32_bf16 v[32:35], v[156:159], v[182:185], v[32:35]
	v_mfma_f32_16x16x32_bf16 v[20:23], v[148:151], v[108:111], v[20:23]
	v_mfma_f32_16x16x32_bf16 v[16:19], v[156:159], v[108:111], v[16:19]
	v_mfma_f32_16x16x32_bf16 v[4:7], v[148:151], v[100:103], v[4:7]
	v_mfma_f32_16x16x32_bf16 v[0:3], v[156:159], v[100:103], v[0:3]
	s_setprio 0
	s_branch .LBB0_585

.LBB0_626:
	s_add_u32 s8, s48, s6
	s_addc_u32 s9, s49, s7
	s_add_u32 s10, s8, 0x100
	s_addc_u32 s11, s9, 0
	s_add_u32 s21, s12, s6
	s_addc_u32 s44, s13, s7
	s_add_i32 s45, 16, 0x10000
	s_cmpk_eq_i32 s6, 0x1500
	s_cselect_b64 s[14:15], -1, 0
	s_and_b64 s[8:9], s[14:15], exec
	s_cselect_b32 s11, s5, s11
	s_cselect_b32 s10, s4, s10
	s_cselect_b32 s9, s29, s44
	s_cselect_b32 s8, s28, s21
	s_add_i32 s21, 16, 0x14000
	v_add_u32_e32 v128, s45, v205
	v_add_u32_e32 v140, s21, v205
	ds_read_b128 v[144:147], v128
	ds_read_b128 v[148:151], v128 offset:1024
	ds_read_b128 v[152:155], v128 offset:2048
	ds_read_b128 v[156:159], v128 offset:3072
	ds_read_b128 v[128:131], v140
	ds_read_b128 v[132:135], v140 offset:1024
	ds_read_b128 v[136:139], v140 offset:2048
	ds_read_b128 v[140:143], v140 offset:3072
	v_lshl_add_u64 v[228:229], v[226:227], 0, s[6:7]
	s_add_i32 m0, s34, 0xc000
	s_waitcnt lgkmcnt(0)
	ds_read_b128 v[162:165], v243
	ds_read_b128 v[166:169], v243 offset:1024
	ds_read_b128 v[170:173], v243 offset:2048
	ds_read_b128 v[174:177], v243 offset:3072
	ds_read_b128 v[178:181], v243 offset:4096
	ds_read_b128 v[182:185], v243 offset:5120
	ds_read_b128 v[186:189], v243 offset:6144
	ds_read_b128 v[190:193], v243 offset:7168
	global_load_lds_dwordx4 v[228:229], off
	v_lshl_add_u64 v[228:229], v[224:225], 0, s[6:7]
	s_add_i32 m0, s34, 0xe000
	s_nop 0
	global_load_lds_dwordx4 v[228:229], off
	s_waitcnt vmcnt(8)
	s_waitcnt lgkmcnt(0)
	s_barrier
	s_setprio 1
	v_mfma_f32_16x16x32_bf16 v[124:127], v[144:147], v[162:165], v[124:127]
	v_mfma_f32_16x16x32_bf16 v[120:123], v[152:155], v[162:165], v[120:123]
	v_mfma_f32_16x16x32_bf16 v[108:111], v[144:147], v[170:173], v[108:111]
	v_mfma_f32_16x16x32_bf16 v[104:107], v[152:155], v[170:173], v[104:107]
	v_mfma_f32_16x16x32_bf16 v[92:95], v[144:147], v[178:181], v[92:95]
	v_mfma_f32_16x16x32_bf16 v[88:91], v[152:155], v[178:181], v[88:91]
	v_mfma_f32_16x16x32_bf16 v[76:79], v[144:147], v[186:189], v[76:79]
	v_mfma_f32_16x16x32_bf16 v[72:75], v[152:155], v[186:189], v[72:75]
	v_mfma_f32_16x16x32_bf16 v[124:127], v[148:151], v[166:169], v[124:127]
	v_mfma_f32_16x16x32_bf16 v[120:123], v[156:159], v[166:169], v[120:123]
	v_mfma_f32_16x16x32_bf16 v[108:111], v[148:151], v[174:177], v[108:111]
	v_mfma_f32_16x16x32_bf16 v[104:107], v[156:159], v[174:177], v[104:107]
	v_mfma_f32_16x16x32_bf16 v[92:95], v[148:151], v[182:185], v[92:95]
	v_mfma_f32_16x16x32_bf16 v[88:91], v[156:159], v[182:185], v[88:91]
	v_mfma_f32_16x16x32_bf16 v[76:79], v[148:151], v[190:193], v[76:79]
	v_mfma_f32_16x16x32_bf16 v[72:75], v[156:159], v[190:193], v[72:75]
	s_setprio 0
	s_setprio 1
	v_mfma_f32_16x16x32_bf16 v[116:119], v[128:131], v[162:165], v[116:119]
	v_mfma_f32_16x16x32_bf16 v[112:115], v[136:139], v[162:165], v[112:115]
	v_mfma_f32_16x16x32_bf16 v[100:103], v[128:131], v[170:173], v[100:103]
	v_mfma_f32_16x16x32_bf16 v[96:99], v[136:139], v[170:173], v[96:99]
	v_mfma_f32_16x16x32_bf16 v[84:87], v[128:131], v[178:181], v[84:87]
	v_mfma_f32_16x16x32_bf16 v[80:83], v[136:139], v[178:181], v[80:83]
	v_mfma_f32_16x16x32_bf16 v[68:71], v[128:131], v[186:189], v[68:71]
	v_mfma_f32_16x16x32_bf16 v[64:67], v[136:139], v[186:189], v[64:67]
	v_mfma_f32_16x16x32_bf16 v[116:119], v[132:135], v[166:169], v[116:119]
	v_mfma_f32_16x16x32_bf16 v[112:115], v[140:143], v[166:169], v[112:115]
	v_mfma_f32_16x16x32_bf16 v[100:103], v[132:135], v[174:177], v[100:103]
	v_mfma_f32_16x16x32_bf16 v[96:99], v[140:143], v[174:177], v[96:99]
	v_mfma_f32_16x16x32_bf16 v[84:87], v[132:135], v[182:185], v[84:87]
	v_mfma_f32_16x16x32_bf16 v[80:83], v[140:143], v[182:185], v[80:83]
	v_mfma_f32_16x16x32_bf16 v[68:71], v[132:135], v[190:193], v[68:71]
	v_mfma_f32_16x16x32_bf16 v[64:67], v[140:143], v[190:193], v[64:67]
	s_setprio 0
	s_barrier
	s_add_i32 s44, s45, s52
	v_lshl_add_u64 v[228:229], s[8:9], 0, v[194:195]
	s_mov_b32 m0, s44
	ds_read_b128 v[186:189], v243 offset:16384
	ds_read_b128 v[190:193], v243 offset:17408
	ds_read_b128 v[178:181], v243 offset:18432
	ds_read_b128 v[182:185], v243 offset:19456
	ds_read_b128 v[170:173], v243 offset:20480
	ds_read_b128 v[174:177], v243 offset:21504
	ds_read_b128 v[162:165], v243 offset:22528
	ds_read_b128 v[166:169], v243 offset:23552
	global_load_lds_dwordx4 v[228:229], off
	s_add_i32 m0, s44, 0x2000
	s_add_u32 s44, s8, 0xb0000
	v_lshl_add_u64 v[230:231], s[8:9], 0, v[196:197]
	s_addc_u32 s45, s9, 0
	s_add_i32 s21, s21, s52
	global_load_lds_dwordx4 v[230:231], off
	v_lshl_add_u64 v[232:233], s[44:45], 0, v[194:195]
	s_mov_b32 m0, s21
	v_lshl_add_u64 v[234:235], s[10:11], 0, v[196:197]
	global_load_lds_dwordx4 v[232:233], off
	v_lshl_add_u64 v[232:233], s[44:45], 0, v[196:197]
	s_add_i32 m0, s21, 0x2000
	v_cndmask_b32_e64 v160, 0, 1, s[0:1]
	global_load_lds_dwordx4 v[232:233], off
	v_lshl_add_u64 v[232:233], s[10:11], 0, v[194:195]
	s_mov_b32 m0, s34
	v_cmp_ne_u32_e64 s[44:45], 1, v160
	global_load_lds_dwordx4 v[232:233], off
	s_mov_b32 m0, s35
	s_andn2_b64 vcc, exec, s[0:1]
	global_load_lds_dwordx4 v[234:235], off
	s_waitcnt vmcnt(8)
	s_waitcnt lgkmcnt(0)
	s_barrier
	s_cbranch_vccnz .LBB0_628
	s_setprio 1
	v_mfma_f32_16x16x32_bf16 v[60:63], v[144:147], v[186:189], v[60:63]
	v_mfma_f32_16x16x32_bf16 v[56:59], v[152:155], v[186:189], v[56:59]
	v_mfma_f32_16x16x32_bf16 v[44:47], v[144:147], v[178:181], v[44:47]
	v_mfma_f32_16x16x32_bf16 v[40:43], v[152:155], v[178:181], v[40:43]
	v_mfma_f32_16x16x32_bf16 v[28:31], v[144:147], v[170:173], v[28:31]
	v_mfma_f32_16x16x32_bf16 v[24:27], v[152:155], v[170:173], v[24:27]
	v_mfma_f32_16x16x32_bf16 v[12:15], v[144:147], v[162:165], v[12:15]
	v_mfma_f32_16x16x32_bf16 v[8:11], v[152:155], v[162:165], v[8:11]
	v_mfma_f32_16x16x32_bf16 v[60:63], v[148:151], v[190:193], v[60:63]
	v_mfma_f32_16x16x32_bf16 v[56:59], v[156:159], v[190:193], v[56:59]
	v_mfma_f32_16x16x32_bf16 v[44:47], v[148:151], v[182:185], v[44:47]
	v_mfma_f32_16x16x32_bf16 v[40:43], v[156:159], v[182:185], v[40:43]
	v_mfma_f32_16x16x32_bf16 v[28:31], v[148:151], v[174:177], v[28:31]
	v_mfma_f32_16x16x32_bf16 v[24:27], v[156:159], v[174:177], v[24:27]
	v_mfma_f32_16x16x32_bf16 v[12:15], v[148:151], v[166:169], v[12:15]
	v_mfma_f32_16x16x32_bf16 v[8:11], v[156:159], v[166:169], v[8:11]
	s_setprio 0
	s_setprio 1
	v_mfma_f32_16x16x32_bf16 v[52:55], v[128:131], v[186:189], v[52:55]
	v_mfma_f32_16x16x32_bf16 v[48:51], v[136:139], v[186:189], v[48:51]
	v_mfma_f32_16x16x32_bf16 v[36:39], v[128:131], v[178:181], v[36:39]
	v_mfma_f32_16x16x32_bf16 v[32:35], v[136:139], v[178:181], v[32:35]
	v_mfma_f32_16x16x32_bf16 v[20:23], v[128:131], v[170:173], v[20:23]
	v_mfma_f32_16x16x32_bf16 v[16:19], v[136:139], v[170:173], v[16:19]
	v_mfma_f32_16x16x32_bf16 v[4:7], v[128:131], v[162:165], v[4:7]
	v_mfma_f32_16x16x32_bf16 v[0:3], v[136:139], v[162:165], v[0:3]
	v_mfma_f32_16x16x32_bf16 v[52:55], v[132:135], v[190:193], v[52:55]
	v_mfma_f32_16x16x32_bf16 v[48:51], v[140:143], v[190:193], v[48:51]
	v_mfma_f32_16x16x32_bf16 v[36:39], v[132:135], v[182:185], v[36:39]
	v_mfma_f32_16x16x32_bf16 v[32:35], v[140:143], v[182:185], v[32:35]
	v_mfma_f32_16x16x32_bf16 v[20:23], v[132:135], v[174:177], v[20:23]
	v_mfma_f32_16x16x32_bf16 v[16:19], v[140:143], v[174:177], v[16:19]
	v_mfma_f32_16x16x32_bf16 v[4:7], v[132:135], v[166:169], v[4:7]
	v_mfma_f32_16x16x32_bf16 v[0:3], v[140:143], v[166:169], v[0:3]
	s_setprio 0
.LBB0_628:
	s_barrier
	s_add_i32 s21, 16, 0x18000
	s_add_i32 s54, 16, 0x1c000
	v_add_u32_e32 v128, s21, v205
	v_add_u32_e32 v140, s54, v205
	ds_read_b128 v[144:147], v128
	ds_read_b128 v[148:151], v128 offset:1024
	ds_read_b128 v[152:155], v128 offset:2048
	ds_read_b128 v[156:159], v128 offset:3072
	ds_read_b128 v[128:131], v140
	ds_read_b128 v[132:135], v140 offset:1024
	ds_read_b128 v[136:139], v140 offset:2048
	ds_read_b128 v[140:143], v140 offset:3072
	s_and_b64 s[14:15], s[46:47], s[14:15]
	s_and_b64 s[14:15], s[14:15], exec
	s_cselect_b32 s15, s3, s64
	s_cselect_b32 s14, 0, 0
	s_add_u32 s10, s10, s15
	s_addc_u32 s11, s11, s14
	s_mov_b32 m0, s38
	v_lshl_add_u64 v[246:247], s[10:11], 0, v[194:195]
	s_waitcnt lgkmcnt(0)
	ds_read_b128 v[162:165], v243 offset:32768
	ds_read_b128 v[166:169], v243 offset:33792
	ds_read_b128 v[170:173], v243 offset:34816
	ds_read_b128 v[174:177], v243 offset:35840
	ds_read_b128 v[178:181], v243 offset:36864
	ds_read_b128 v[182:185], v243 offset:37888
	ds_read_b128 v[186:189], v243 offset:38912
	ds_read_b128 v[190:193], v243 offset:39936
	global_load_lds_dwordx4 v[246:247], off
	v_lshl_add_u64 v[246:247], s[10:11], 0, v[196:197]
	s_mov_b32 m0, s39
	s_nop 0
	global_load_lds_dwordx4 v[246:247], off
	s_waitcnt vmcnt(8)
	s_waitcnt lgkmcnt(0)
	s_barrier
	s_setprio 1
	v_mfma_f32_16x16x32_bf16 v[124:127], v[144:147], v[162:165], v[124:127]
	v_mfma_f32_16x16x32_bf16 v[120:123], v[152:155], v[162:165], v[120:123]
	v_mfma_f32_16x16x32_bf16 v[108:111], v[144:147], v[170:173], v[108:111]
	v_mfma_f32_16x16x32_bf16 v[104:107], v[152:155], v[170:173], v[104:107]
	v_mfma_f32_16x16x32_bf16 v[92:95], v[144:147], v[178:181], v[92:95]
	v_mfma_f32_16x16x32_bf16 v[88:91], v[152:155], v[178:181], v[88:91]
	v_mfma_f32_16x16x32_bf16 v[76:79], v[144:147], v[186:189], v[76:79]
	v_mfma_f32_16x16x32_bf16 v[72:75], v[152:155], v[186:189], v[72:75]
	v_mfma_f32_16x16x32_bf16 v[124:127], v[148:151], v[166:169], v[124:127]
	v_mfma_f32_16x16x32_bf16 v[120:123], v[156:159], v[166:169], v[120:123]
	v_mfma_f32_16x16x32_bf16 v[108:111], v[148:151], v[174:177], v[108:111]
	v_mfma_f32_16x16x32_bf16 v[104:107], v[156:159], v[174:177], v[104:107]
	v_mfma_f32_16x16x32_bf16 v[92:95], v[148:151], v[182:185], v[92:95]
	v_mfma_f32_16x16x32_bf16 v[88:91], v[156:159], v[182:185], v[88:91]
	v_mfma_f32_16x16x32_bf16 v[76:79], v[148:151], v[190:193], v[76:79]
	v_mfma_f32_16x16x32_bf16 v[72:75], v[156:159], v[190:193], v[72:75]
	s_setprio 0
	s_setprio 1
	v_mfma_f32_16x16x32_bf16 v[116:119], v[128:131], v[162:165], v[116:119]
	v_mfma_f32_16x16x32_bf16 v[112:115], v[136:139], v[162:165], v[112:115]
	v_mfma_f32_16x16x32_bf16 v[100:103], v[128:131], v[170:173], v[100:103]
	v_mfma_f32_16x16x32_bf16 v[96:99], v[136:139], v[170:173], v[96:99]
	v_mfma_f32_16x16x32_bf16 v[84:87], v[128:131], v[178:181], v[84:87]
	v_mfma_f32_16x16x32_bf16 v[80:83], v[136:139], v[178:181], v[80:83]
	v_mfma_f32_16x16x32_bf16 v[68:71], v[128:131], v[186:189], v[68:71]
	v_mfma_f32_16x16x32_bf16 v[64:67], v[136:139], v[186:189], v[64:67]
	v_mfma_f32_16x16x32_bf16 v[116:119], v[132:135], v[166:169], v[116:119]
	v_mfma_f32_16x16x32_bf16 v[112:115], v[140:143], v[166:169], v[112:115]
	v_mfma_f32_16x16x32_bf16 v[100:103], v[132:135], v[174:177], v[100:103]
	v_mfma_f32_16x16x32_bf16 v[96:99], v[140:143], v[174:177], v[96:99]
	v_mfma_f32_16x16x32_bf16 v[84:87], v[132:135], v[182:185], v[84:87]
	v_mfma_f32_16x16x32_bf16 v[80:83], v[140:143], v[182:185], v[80:83]
	v_mfma_f32_16x16x32_bf16 v[68:71], v[132:135], v[190:193], v[68:71]
	v_mfma_f32_16x16x32_bf16 v[64:67], v[140:143], v[190:193], v[64:67]
	s_setprio 0
	s_barrier
	s_add_i32 s10, s21, s52
	v_lshl_add_u64 v[228:229], v[228:229], 0, s[84:85]
	s_mov_b32 m0, s10
	ds_read_b128 v[186:189], v243 offset:49152
	ds_read_b128 v[190:193], v243 offset:50176
	ds_read_b128 v[178:181], v243 offset:51200
	ds_read_b128 v[182:185], v243 offset:52224
	ds_read_b128 v[170:173], v243 offset:53248
	ds_read_b128 v[174:177], v243 offset:54272
	ds_read_b128 v[162:165], v243 offset:55296
	ds_read_b128 v[166:169], v243 offset:56320
	global_load_lds_dwordx4 v[228:229], off
	s_add_i32 m0, s10, 0x2000
	s_add_u32 s8, s8, 0xb0080
	v_lshl_add_u64 v[228:229], v[230:231], 0, s[84:85]
	s_addc_u32 s9, s9, 0
	s_add_i32 s10, s54, s52
	global_load_lds_dwordx4 v[228:229], off
	v_lshl_add_u64 v[228:229], s[8:9], 0, v[194:195]
	s_mov_b32 m0, s10
	s_and_b64 vcc, exec, s[44:45]
	global_load_lds_dwordx4 v[228:229], off
	v_lshl_add_u64 v[228:229], s[8:9], 0, v[196:197]
	s_add_i32 m0, s10, 0x2000
	s_nop 0
	global_load_lds_dwordx4 v[228:229], off
	v_lshl_add_u64 v[228:229], v[232:233], 0, s[84:85]
	s_mov_b32 m0, s53
	s_nop 0
	global_load_lds_dwordx4 v[228:229], off
	v_lshl_add_u64 v[228:229], v[234:235], 0, s[84:85]
	s_mov_b32 m0, s40
	s_nop 0
	global_load_lds_dwordx4 v[228:229], off
	s_waitcnt vmcnt(8)
	s_waitcnt lgkmcnt(0)
	s_barrier
	s_cbranch_vccnz .LBB0_625
	s_setprio 1
	v_mfma_f32_16x16x32_bf16 v[60:63], v[144:147], v[186:189], v[60:63]
	v_mfma_f32_16x16x32_bf16 v[56:59], v[152:155], v[186:189], v[56:59]
	v_mfma_f32_16x16x32_bf16 v[44:47], v[144:147], v[178:181], v[44:47]
	v_mfma_f32_16x16x32_bf16 v[40:43], v[152:155], v[178:181], v[40:43]
	v_mfma_f32_16x16x32_bf16 v[28:31], v[144:147], v[170:173], v[28:31]
	v_mfma_f32_16x16x32_bf16 v[24:27], v[152:155], v[170:173], v[24:27]
	v_mfma_f32_16x16x32_bf16 v[12:15], v[144:147], v[162:165], v[12:15]
	v_mfma_f32_16x16x32_bf16 v[8:11], v[152:155], v[162:165], v[8:11]
	v_mfma_f32_16x16x32_bf16 v[60:63], v[148:151], v[190:193], v[60:63]
	v_mfma_f32_16x16x32_bf16 v[56:59], v[156:159], v[190:193], v[56:59]
	v_mfma_f32_16x16x32_bf16 v[44:47], v[148:151], v[182:185], v[44:47]
	v_mfma_f32_16x16x32_bf16 v[40:43], v[156:159], v[182:185], v[40:43]
	v_mfma_f32_16x16x32_bf16 v[28:31], v[148:151], v[174:177], v[28:31]
	v_mfma_f32_16x16x32_bf16 v[24:27], v[156:159], v[174:177], v[24:27]
	v_mfma_f32_16x16x32_bf16 v[12:15], v[148:151], v[166:169], v[12:15]
	v_mfma_f32_16x16x32_bf16 v[8:11], v[156:159], v[166:169], v[8:11]
	s_setprio 0
	s_setprio 1
	v_mfma_f32_16x16x32_bf16 v[52:55], v[128:131], v[186:189], v[52:55]
	v_mfma_f32_16x16x32_bf16 v[48:51], v[136:139], v[186:189], v[48:51]
	v_mfma_f32_16x16x32_bf16 v[36:39], v[128:131], v[178:181], v[36:39]
	v_mfma_f32_16x16x32_bf16 v[32:35], v[136:139], v[178:181], v[32:35]
	v_mfma_f32_16x16x32_bf16 v[20:23], v[128:131], v[170:173], v[20:23]
	v_mfma_f32_16x16x32_bf16 v[16:19], v[136:139], v[170:173], v[16:19]
	v_mfma_f32_16x16x32_bf16 v[4:7], v[128:131], v[162:165], v[4:7]
	v_mfma_f32_16x16x32_bf16 v[0:3], v[136:139], v[162:165], v[0:3]
	v_mfma_f32_16x16x32_bf16 v[52:55], v[132:135], v[190:193], v[52:55]
	v_mfma_f32_16x16x32_bf16 v[48:51], v[140:143], v[190:193], v[48:51]
	v_mfma_f32_16x16x32_bf16 v[36:39], v[132:135], v[182:185], v[36:39]
	v_mfma_f32_16x16x32_bf16 v[32:35], v[140:143], v[182:185], v[32:35]
	v_mfma_f32_16x16x32_bf16 v[20:23], v[132:135], v[174:177], v[20:23]
	v_mfma_f32_16x16x32_bf16 v[16:19], v[140:143], v[174:177], v[16:19]
	v_mfma_f32_16x16x32_bf16 v[4:7], v[132:135], v[166:169], v[4:7]
	v_mfma_f32_16x16x32_bf16 v[0:3], v[140:143], v[166:169], v[0:3]
	s_setprio 0
	s_branch .LBB0_625

.LBB0_722:
	s_add_u32 s0, s2, s6
	s_addc_u32 s1, s3, s7
	s_add_u32 s8, s0, 0x100
	s_addc_u32 s9, s1, 0
	s_add_u32 s55, s96, s6
	s_addc_u32 vcc_lo, s97, s7
	s_add_i32 vcc_hi, 16, 0x10000
	s_cmpk_eq_i32 s6, 0x700
	s_cselect_b64 s[38:39], -1, 0
	s_and_b64 s[0:1], s[38:39], exec
	s_cselect_b32 s11, s17, s9
	s_cselect_b32 s10, s29, s8
	s_cselect_b32 s9, s13, vcc_lo
	s_cselect_b32 s8, s31, s55
	s_add_i32 s55, 16, 0x14000
	v_add_u32_e32 v128, vcc_hi, v203
	v_add_u32_e32 v140, s55, v203
	ds_read_b128 v[144:147], v128
	ds_read_b128 v[148:151], v128 offset:1024
	ds_read_b128 v[152:155], v128 offset:2048
	ds_read_b128 v[156:159], v128 offset:3072
	ds_read_b128 v[128:131], v140
	ds_read_b128 v[132:135], v140 offset:1024
	ds_read_b128 v[136:139], v140 offset:2048
	ds_read_b128 v[140:143], v140 offset:3072
	v_lshl_add_u64 v[214:215], v[212:213], 0, s[6:7]
	s_add_i32 m0, s21, 0xc000
	s_waitcnt lgkmcnt(0)
	ds_read_b128 v[162:165], v223
	ds_read_b128 v[166:169], v223 offset:1024
	ds_read_b128 v[170:173], v223 offset:2048
	ds_read_b128 v[174:177], v223 offset:3072
	ds_read_b128 v[178:181], v223 offset:4096
	ds_read_b128 v[182:185], v223 offset:5120
	ds_read_b128 v[186:189], v223 offset:6144
	ds_read_b128 v[190:193], v223 offset:7168
	global_load_lds_dwordx4 v[214:215], off
	v_lshl_add_u64 v[214:215], v[210:211], 0, s[6:7]
	s_add_i32 m0, s21, 0xe000
	s_nop 0
	global_load_lds_dwordx4 v[214:215], off
	s_waitcnt vmcnt(8)
	s_waitcnt lgkmcnt(0)
	s_barrier
	s_setprio 1
	v_mfma_f32_16x16x32_bf16 v[124:127], v[144:147], v[162:165], v[124:127]
	v_mfma_f32_16x16x32_bf16 v[120:123], v[152:155], v[162:165], v[120:123]
	v_mfma_f32_16x16x32_bf16 v[108:111], v[144:147], v[170:173], v[108:111]
	v_mfma_f32_16x16x32_bf16 v[104:107], v[152:155], v[170:173], v[104:107]
	v_mfma_f32_16x16x32_bf16 v[92:95], v[144:147], v[178:181], v[92:95]
	v_mfma_f32_16x16x32_bf16 v[88:91], v[152:155], v[178:181], v[88:91]
	v_mfma_f32_16x16x32_bf16 v[76:79], v[144:147], v[186:189], v[76:79]
	v_mfma_f32_16x16x32_bf16 v[72:75], v[152:155], v[186:189], v[72:75]
	v_mfma_f32_16x16x32_bf16 v[124:127], v[148:151], v[166:169], v[124:127]
	v_mfma_f32_16x16x32_bf16 v[120:123], v[156:159], v[166:169], v[120:123]
	v_mfma_f32_16x16x32_bf16 v[108:111], v[148:151], v[174:177], v[108:111]
	v_mfma_f32_16x16x32_bf16 v[104:107], v[156:159], v[174:177], v[104:107]
	v_mfma_f32_16x16x32_bf16 v[92:95], v[148:151], v[182:185], v[92:95]
	v_mfma_f32_16x16x32_bf16 v[88:91], v[156:159], v[182:185], v[88:91]
	v_mfma_f32_16x16x32_bf16 v[76:79], v[148:151], v[190:193], v[76:79]
	v_mfma_f32_16x16x32_bf16 v[72:75], v[156:159], v[190:193], v[72:75]
	s_setprio 0
	s_setprio 1
	v_mfma_f32_16x16x32_bf16 v[116:119], v[128:131], v[162:165], v[116:119]
	v_mfma_f32_16x16x32_bf16 v[112:115], v[136:139], v[162:165], v[112:115]
	v_mfma_f32_16x16x32_bf16 v[100:103], v[128:131], v[170:173], v[100:103]
	v_mfma_f32_16x16x32_bf16 v[96:99], v[136:139], v[170:173], v[96:99]
	v_mfma_f32_16x16x32_bf16 v[84:87], v[128:131], v[178:181], v[84:87]
	v_mfma_f32_16x16x32_bf16 v[80:83], v[136:139], v[178:181], v[80:83]
	v_mfma_f32_16x16x32_bf16 v[68:71], v[128:131], v[186:189], v[68:71]
	v_mfma_f32_16x16x32_bf16 v[64:67], v[136:139], v[186:189], v[64:67]
	v_mfma_f32_16x16x32_bf16 v[116:119], v[132:135], v[166:169], v[116:119]
	v_mfma_f32_16x16x32_bf16 v[112:115], v[140:143], v[166:169], v[112:115]
	v_mfma_f32_16x16x32_bf16 v[100:103], v[132:135], v[174:177], v[100:103]
	v_mfma_f32_16x16x32_bf16 v[96:99], v[140:143], v[174:177], v[96:99]
	v_mfma_f32_16x16x32_bf16 v[84:87], v[132:135], v[182:185], v[84:87]
	v_mfma_f32_16x16x32_bf16 v[80:83], v[140:143], v[182:185], v[80:83]
	v_mfma_f32_16x16x32_bf16 v[68:71], v[132:135], v[190:193], v[68:71]
	v_mfma_f32_16x16x32_bf16 v[64:67], v[140:143], v[190:193], v[64:67]
	s_setprio 0
	s_barrier
	s_add_i32 s0, vcc_hi, s20
	v_lshl_add_u64 v[214:215], s[8:9], 0, v[198:199]
	s_mov_b32 m0, s0
	ds_read_b128 v[186:189], v223 offset:16384
	ds_read_b128 v[190:193], v223 offset:17408
	ds_read_b128 v[178:181], v223 offset:18432
	ds_read_b128 v[182:185], v223 offset:19456
	ds_read_b128 v[170:173], v223 offset:20480
	ds_read_b128 v[174:177], v223 offset:21504
	ds_read_b128 v[162:165], v223 offset:22528
	ds_read_b128 v[166:169], v223 offset:23552
	global_load_lds_dwordx4 v[214:215], off
	s_add_i32 m0, s0, 0x2000
	s_add_u32 s0, s8, 0x40000
	v_lshl_add_u64 v[216:217], s[8:9], 0, v[194:195]
	s_addc_u32 s1, s9, 0
	s_add_i32 s55, s55, s20
	global_load_lds_dwordx4 v[216:217], off
	v_lshl_add_u64 v[218:219], s[0:1], 0, v[198:199]
	s_mov_b32 m0, s55
	v_lshl_add_u64 v[220:221], s[10:11], 0, v[196:197]
	global_load_lds_dwordx4 v[218:219], off
	v_lshl_add_u64 v[218:219], s[0:1], 0, v[194:195]
	s_add_i32 m0, s55, 0x2000
	v_cndmask_b32_e64 v160, 0, 1, s[4:5]
	global_load_lds_dwordx4 v[218:219], off
	v_lshl_add_u64 v[218:219], s[10:11], 0, v[200:201]
	s_mov_b32 m0, s21
	v_cmp_ne_u32_e64 s[0:1], 1, v160
	global_load_lds_dwordx4 v[218:219], off
	s_mov_b32 m0, s42
	s_andn2_b64 vcc, exec, s[4:5]
	global_load_lds_dwordx4 v[220:221], off
	s_waitcnt vmcnt(8)
	s_waitcnt lgkmcnt(0)
	s_barrier
	s_cbranch_vccnz .LBB0_724
	s_setprio 1
	v_mfma_f32_16x16x32_bf16 v[60:63], v[144:147], v[186:189], v[60:63]
	v_mfma_f32_16x16x32_bf16 v[56:59], v[152:155], v[186:189], v[56:59]
	v_mfma_f32_16x16x32_bf16 v[44:47], v[144:147], v[178:181], v[44:47]
	v_mfma_f32_16x16x32_bf16 v[40:43], v[152:155], v[178:181], v[40:43]
	v_mfma_f32_16x16x32_bf16 v[28:31], v[144:147], v[170:173], v[28:31]
	v_mfma_f32_16x16x32_bf16 v[24:27], v[152:155], v[170:173], v[24:27]
	v_mfma_f32_16x16x32_bf16 v[12:15], v[144:147], v[162:165], v[12:15]
	v_mfma_f32_16x16x32_bf16 v[8:11], v[152:155], v[162:165], v[8:11]
	v_mfma_f32_16x16x32_bf16 v[60:63], v[148:151], v[190:193], v[60:63]
	v_mfma_f32_16x16x32_bf16 v[56:59], v[156:159], v[190:193], v[56:59]
	v_mfma_f32_16x16x32_bf16 v[44:47], v[148:151], v[182:185], v[44:47]
	v_mfma_f32_16x16x32_bf16 v[40:43], v[156:159], v[182:185], v[40:43]
	v_mfma_f32_16x16x32_bf16 v[28:31], v[148:151], v[174:177], v[28:31]
	v_mfma_f32_16x16x32_bf16 v[24:27], v[156:159], v[174:177], v[24:27]
	v_mfma_f32_16x16x32_bf16 v[12:15], v[148:151], v[166:169], v[12:15]
	v_mfma_f32_16x16x32_bf16 v[8:11], v[156:159], v[166:169], v[8:11]
	s_setprio 0
	s_setprio 1
	v_mfma_f32_16x16x32_bf16 v[52:55], v[128:131], v[186:189], v[52:55]
	v_mfma_f32_16x16x32_bf16 v[48:51], v[136:139], v[186:189], v[48:51]
	v_mfma_f32_16x16x32_bf16 v[36:39], v[128:131], v[178:181], v[36:39]
	v_mfma_f32_16x16x32_bf16 v[32:35], v[136:139], v[178:181], v[32:35]
	v_mfma_f32_16x16x32_bf16 v[20:23], v[128:131], v[170:173], v[20:23]
	v_mfma_f32_16x16x32_bf16 v[16:19], v[136:139], v[170:173], v[16:19]
	v_mfma_f32_16x16x32_bf16 v[4:7], v[128:131], v[162:165], v[4:7]
	v_mfma_f32_16x16x32_bf16 v[0:3], v[136:139], v[162:165], v[0:3]
	v_mfma_f32_16x16x32_bf16 v[52:55], v[132:135], v[190:193], v[52:55]
	v_mfma_f32_16x16x32_bf16 v[48:51], v[140:143], v[190:193], v[48:51]
	v_mfma_f32_16x16x32_bf16 v[36:39], v[132:135], v[182:185], v[36:39]
	v_mfma_f32_16x16x32_bf16 v[32:35], v[140:143], v[182:185], v[32:35]
	v_mfma_f32_16x16x32_bf16 v[20:23], v[132:135], v[174:177], v[20:23]
	v_mfma_f32_16x16x32_bf16 v[16:19], v[140:143], v[174:177], v[16:19]
	v_mfma_f32_16x16x32_bf16 v[4:7], v[132:135], v[166:169], v[4:7]
	v_mfma_f32_16x16x32_bf16 v[0:3], v[140:143], v[166:169], v[0:3]
	s_setprio 0
.LBB0_724:
	s_barrier
	s_add_i32 s55, 16, 0x18000
	s_add_i32 vcc_lo, 16, 0x1c000
	v_add_u32_e32 v128, s55, v203
	v_add_u32_e32 v140, vcc_lo, v203
	ds_read_b128 v[144:147], v128
	ds_read_b128 v[148:151], v128 offset:1024
	ds_read_b128 v[152:155], v128 offset:2048
	ds_read_b128 v[156:159], v128 offset:3072
	ds_read_b128 v[128:131], v140
	ds_read_b128 v[132:135], v140 offset:1024
	ds_read_b128 v[136:139], v140 offset:2048
	ds_read_b128 v[140:143], v140 offset:3072
	s_and_b64 s[38:39], s[36:37], s[38:39]
	s_and_b64 s[38:39], s[38:39], exec
	s_cselect_b32 s39, s12, s64
	s_cselect_b32 s38, 0, 0
	s_add_u32 s10, s10, s39
	s_addc_u32 s11, s11, s38
	s_mov_b32 m0, s43
	v_lshl_add_u64 v[224:225], s[10:11], 0, v[200:201]
	s_waitcnt lgkmcnt(0)
	ds_read_b128 v[162:165], v223 offset:32768
	ds_read_b128 v[166:169], v223 offset:33792
	ds_read_b128 v[170:173], v223 offset:34816
	ds_read_b128 v[174:177], v223 offset:35840
	ds_read_b128 v[178:181], v223 offset:36864
	ds_read_b128 v[182:185], v223 offset:37888
	ds_read_b128 v[186:189], v223 offset:38912
	ds_read_b128 v[190:193], v223 offset:39936
	global_load_lds_dwordx4 v[224:225], off
	v_lshl_add_u64 v[224:225], s[10:11], 0, v[196:197]
	s_mov_b32 m0, s44
	s_nop 0
	global_load_lds_dwordx4 v[224:225], off
	s_waitcnt vmcnt(8)
	s_waitcnt lgkmcnt(0)
	s_barrier
	s_setprio 1
	v_mfma_f32_16x16x32_bf16 v[124:127], v[144:147], v[162:165], v[124:127]
	v_mfma_f32_16x16x32_bf16 v[120:123], v[152:155], v[162:165], v[120:123]
	v_mfma_f32_16x16x32_bf16 v[108:111], v[144:147], v[170:173], v[108:111]
	v_mfma_f32_16x16x32_bf16 v[104:107], v[152:155], v[170:173], v[104:107]
	v_mfma_f32_16x16x32_bf16 v[92:95], v[144:147], v[178:181], v[92:95]
	v_mfma_f32_16x16x32_bf16 v[88:91], v[152:155], v[178:181], v[88:91]
	v_mfma_f32_16x16x32_bf16 v[76:79], v[144:147], v[186:189], v[76:79]
	v_mfma_f32_16x16x32_bf16 v[72:75], v[152:155], v[186:189], v[72:75]
	v_mfma_f32_16x16x32_bf16 v[124:127], v[148:151], v[166:169], v[124:127]
	v_mfma_f32_16x16x32_bf16 v[120:123], v[156:159], v[166:169], v[120:123]
	v_mfma_f32_16x16x32_bf16 v[108:111], v[148:151], v[174:177], v[108:111]
	v_mfma_f32_16x16x32_bf16 v[104:107], v[156:159], v[174:177], v[104:107]
	v_mfma_f32_16x16x32_bf16 v[92:95], v[148:151], v[182:185], v[92:95]
	v_mfma_f32_16x16x32_bf16 v[88:91], v[156:159], v[182:185], v[88:91]
	v_mfma_f32_16x16x32_bf16 v[76:79], v[148:151], v[190:193], v[76:79]
	v_mfma_f32_16x16x32_bf16 v[72:75], v[156:159], v[190:193], v[72:75]
	s_setprio 0
	s_setprio 1
	v_mfma_f32_16x16x32_bf16 v[116:119], v[128:131], v[162:165], v[116:119]
	v_mfma_f32_16x16x32_bf16 v[112:115], v[136:139], v[162:165], v[112:115]
	v_mfma_f32_16x16x32_bf16 v[100:103], v[128:131], v[170:173], v[100:103]
	v_mfma_f32_16x16x32_bf16 v[96:99], v[136:139], v[170:173], v[96:99]
	v_mfma_f32_16x16x32_bf16 v[84:87], v[128:131], v[178:181], v[84:87]
	v_mfma_f32_16x16x32_bf16 v[80:83], v[136:139], v[178:181], v[80:83]
	v_mfma_f32_16x16x32_bf16 v[68:71], v[128:131], v[186:189], v[68:71]
	v_mfma_f32_16x16x32_bf16 v[64:67], v[136:139], v[186:189], v[64:67]
	v_mfma_f32_16x16x32_bf16 v[116:119], v[132:135], v[166:169], v[116:119]
	v_mfma_f32_16x16x32_bf16 v[112:115], v[140:143], v[166:169], v[112:115]
	v_mfma_f32_16x16x32_bf16 v[100:103], v[132:135], v[174:177], v[100:103]
	v_mfma_f32_16x16x32_bf16 v[96:99], v[140:143], v[174:177], v[96:99]
	v_mfma_f32_16x16x32_bf16 v[84:87], v[132:135], v[182:185], v[84:87]
	v_mfma_f32_16x16x32_bf16 v[80:83], v[140:143], v[182:185], v[80:83]
	v_mfma_f32_16x16x32_bf16 v[68:71], v[132:135], v[190:193], v[68:71]
	v_mfma_f32_16x16x32_bf16 v[64:67], v[140:143], v[190:193], v[64:67]
	s_setprio 0
	s_barrier
	s_add_i32 s10, s55, s20
	v_lshl_add_u64 v[214:215], v[214:215], 0, s[84:85]
	s_mov_b32 m0, s10
	ds_read_b128 v[186:189], v223 offset:49152
	ds_read_b128 v[190:193], v223 offset:50176
	ds_read_b128 v[178:181], v223 offset:51200
	ds_read_b128 v[182:185], v223 offset:52224
	ds_read_b128 v[170:173], v223 offset:53248
	ds_read_b128 v[174:177], v223 offset:54272
	ds_read_b128 v[162:165], v223 offset:55296
	ds_read_b128 v[166:169], v223 offset:56320
	global_load_lds_dwordx4 v[214:215], off
	s_add_i32 m0, s10, 0x2000
	s_add_u32 s8, s8, 0x40080
	v_lshl_add_u64 v[214:215], v[216:217], 0, s[84:85]
	s_addc_u32 s9, s9, 0
	s_add_i32 s10, vcc_lo, s20
	global_load_lds_dwordx4 v[214:215], off
	v_lshl_add_u64 v[214:215], s[8:9], 0, v[198:199]
	s_mov_b32 m0, s10
	s_and_b64 vcc, exec, s[0:1]
	global_load_lds_dwordx4 v[214:215], off
	v_lshl_add_u64 v[214:215], s[8:9], 0, v[194:195]
	s_add_i32 m0, s10, 0x2000
	s_nop 0
	global_load_lds_dwordx4 v[214:215], off
	v_lshl_add_u64 v[214:215], v[218:219], 0, s[84:85]
	s_mov_b32 m0, s47
	s_nop 0
	global_load_lds_dwordx4 v[214:215], off
	v_lshl_add_u64 v[214:215], v[220:221], 0, s[84:85]
	s_mov_b32 m0, s48
	s_nop 0
	global_load_lds_dwordx4 v[214:215], off
	s_waitcnt vmcnt(8)
	s_waitcnt lgkmcnt(0)
	s_barrier
	s_cbranch_vccnz .LBB0_721
	s_setprio 1
	v_mfma_f32_16x16x32_bf16 v[60:63], v[144:147], v[186:189], v[60:63]
	v_mfma_f32_16x16x32_bf16 v[56:59], v[152:155], v[186:189], v[56:59]
	v_mfma_f32_16x16x32_bf16 v[44:47], v[144:147], v[178:181], v[44:47]
	v_mfma_f32_16x16x32_bf16 v[40:43], v[152:155], v[178:181], v[40:43]
	v_mfma_f32_16x16x32_bf16 v[28:31], v[144:147], v[170:173], v[28:31]
	v_mfma_f32_16x16x32_bf16 v[24:27], v[152:155], v[170:173], v[24:27]
	v_mfma_f32_16x16x32_bf16 v[12:15], v[144:147], v[162:165], v[12:15]
	v_mfma_f32_16x16x32_bf16 v[8:11], v[152:155], v[162:165], v[8:11]
	v_mfma_f32_16x16x32_bf16 v[60:63], v[148:151], v[190:193], v[60:63]
	v_mfma_f32_16x16x32_bf16 v[56:59], v[156:159], v[190:193], v[56:59]
	v_mfma_f32_16x16x32_bf16 v[44:47], v[148:151], v[182:185], v[44:47]
	v_mfma_f32_16x16x32_bf16 v[40:43], v[156:159], v[182:185], v[40:43]
	v_mfma_f32_16x16x32_bf16 v[28:31], v[148:151], v[174:177], v[28:31]
	v_mfma_f32_16x16x32_bf16 v[24:27], v[156:159], v[174:177], v[24:27]
	v_mfma_f32_16x16x32_bf16 v[12:15], v[148:151], v[166:169], v[12:15]
	v_mfma_f32_16x16x32_bf16 v[8:11], v[156:159], v[166:169], v[8:11]
	s_setprio 0
	s_setprio 1
	v_mfma_f32_16x16x32_bf16 v[52:55], v[128:131], v[186:189], v[52:55]
	v_mfma_f32_16x16x32_bf16 v[48:51], v[136:139], v[186:189], v[48:51]
	v_mfma_f32_16x16x32_bf16 v[36:39], v[128:131], v[178:181], v[36:39]
	v_mfma_f32_16x16x32_bf16 v[32:35], v[136:139], v[178:181], v[32:35]
	v_mfma_f32_16x16x32_bf16 v[20:23], v[128:131], v[170:173], v[20:23]
	v_mfma_f32_16x16x32_bf16 v[16:19], v[136:139], v[170:173], v[16:19]
	v_mfma_f32_16x16x32_bf16 v[4:7], v[128:131], v[162:165], v[4:7]
	v_mfma_f32_16x16x32_bf16 v[0:3], v[136:139], v[162:165], v[0:3]
	v_mfma_f32_16x16x32_bf16 v[52:55], v[132:135], v[190:193], v[52:55]
	v_mfma_f32_16x16x32_bf16 v[48:51], v[140:143], v[190:193], v[48:51]
	v_mfma_f32_16x16x32_bf16 v[36:39], v[132:135], v[182:185], v[36:39]
	v_mfma_f32_16x16x32_bf16 v[32:35], v[140:143], v[182:185], v[32:35]
	v_mfma_f32_16x16x32_bf16 v[20:23], v[132:135], v[174:177], v[20:23]
	v_mfma_f32_16x16x32_bf16 v[16:19], v[140:143], v[174:177], v[16:19]
	v_mfma_f32_16x16x32_bf16 v[4:7], v[132:135], v[166:169], v[4:7]
	v_mfma_f32_16x16x32_bf16 v[0:3], v[140:143], v[166:169], v[0:3]
	s_setprio 0
	s_branch .LBB0_721
